# GEMM mainloops: per-phase priority flips deleted, one static priority raise for waves 4-7
# baseline (speedup 1.0000x reference)
.LBB0_21:
	s_setprio 0
	s_load_dwordx16 s[4:19], s[22:23], 0x0
	s_add_u32 s80, s0, 0x2980000
	s_addc_u32 s81, s1, 0
	s_add_u32 s78, s0, 0x80000
	s_addc_u32 s79, s1, 0
	s_waitcnt lgkmcnt(0)
	v_writelane_b32 v254, s4, 14
	s_cmp_lg_u32 s74, 0
	s_cselect_b64 s[24:25], -1, 0
	v_writelane_b32 v254, s5, 15
	v_writelane_b32 v254, s6, 16
	v_writelane_b32 v254, s7, 17
	v_writelane_b32 v254, s8, 18
	v_writelane_b32 v254, s9, 19
	v_writelane_b32 v254, s10, 20
	v_writelane_b32 v254, s11, 21
	v_writelane_b32 v254, s12, 22
	v_writelane_b32 v254, s13, 23
	v_writelane_b32 v254, s14, 24
	v_writelane_b32 v254, s15, 25
	v_writelane_b32 v254, s16, 26
	v_writelane_b32 v254, s17, 27
	v_writelane_b32 v254, s18, 28
	v_writelane_b32 v254, s19, 29
	s_load_dwordx16 s[4:19], s[22:23], 0x40
	v_and_b32_e32 v218, 63, v233
	s_and_b64 vcc, exec, s[24:25]
	s_waitcnt lgkmcnt(0)
	v_writelane_b32 v254, s4, 30
	s_nop 1
	v_writelane_b32 v254, s5, 31
	v_writelane_b32 v254, s6, 32
	v_writelane_b32 v254, s7, 33
	v_writelane_b32 v254, s8, 34
	v_writelane_b32 v254, s9, 35
	v_writelane_b32 v254, s10, 36
	v_writelane_b32 v254, s11, 37
	v_writelane_b32 v254, s12, 38
	v_writelane_b32 v254, s13, 39
	v_writelane_b32 v254, s14, 40
	v_writelane_b32 v254, s15, 41
	v_writelane_b32 v254, s16, 42
	v_writelane_b32 v254, s17, 43
	v_writelane_b32 v254, s18, 44
	v_writelane_b32 v254, s19, 45
	s_cbranch_vccz .LBB0_27
	v_writelane_b32 v254, s21, 46
	v_writelane_b32 v254, s52, 47
	s_add_u32 s90, s0, 0x6200000
	s_addc_u32 s91, s1, 0
	v_writelane_b32 v254, s53, 48
	v_writelane_b32 v254, s22, 49
	s_load_dword s4, s[22:23], 0x90
	s_add_u32 s82, s0, 0xa200000
	s_addc_u32 s83, s1, 0
	s_add_u32 s84, s0, 0xc200000
	v_writelane_b32 v254, s23, 50
	s_addc_u32 s85, s1, 0
	s_waitcnt lgkmcnt(0)
	v_writelane_b32 v254, s4, 51
	s_mov_b64 s[8:9], -1
	s_mov_b64 s[4:5], 0
	s_cmp_lt_i32 s74, 2
	s_mov_b64 s[6:7], 0
	s_cbranch_scc1 .LBB0_83
	s_cmp_eq_u32 s74, 2
	s_mov_b64 s[6:7], -1
	s_cbranch_scc0 .LBB0_82
	s_cmpk_lg_i32 s98, 0x100
	s_mov_b64 s[6:7], 0
	s_cbranch_scc1 .LBB0_28
	v_readlane_b32 s6, v254, 49
	v_readlane_b32 s7, v254, 50
	s_load_dword s6, s[6:7], 0x88
	s_waitcnt lgkmcnt(0)
	s_cmp_lt_i32 s6, 2
	s_cselect_b64 s[6:7], -1, 0
	s_andn2_b64 vcc, exec, s[6:7]
	s_cbranch_vccz .LBB0_29

.LBB0_278:
	s_or_b64 exec, exec, s[10:11]
	v_bfe_i32 v3, v234, 27, 1
	v_lshlrev_b32_e32 v6, 4, v234
	v_lshrrev_b32_e32 v3, 22, v3
	v_ashrrev_i32_e32 v2, 31, v234
	v_add_u32_e32 v3, v6, v3
	v_lshrrev_b32_e32 v2, 26, v2
	v_and_b32_e32 v3, 0xfffffc00, v3
	s_sub_i32 s9, 2, s29
	v_add_u32_e32 v2, v234, v2
	v_sub_u32_e32 v3, v6, v3
	s_mul_hi_i32 s10, s9, 0x600000
	s_mul_i32 s9, s9, 0x600000
	v_ashrrev_i32_e32 v2, 6, v2
	v_lshrrev_b32_e32 v4, 4, v3
	s_add_u32 s9, s0, s9
	v_bitop3_b32 v4, v4, v3, 32 bitop3:0x6c
	v_lshlrev_b32_e32 v3, 3, v2
	s_addc_u32 s10, s1, s10
	v_and_b32_e32 v7, -16, v3
	v_ashrrev_i32_e32 v3, 31, v4
	s_add_u32 s40, s9, 0x500000
	v_lshrrev_b32_e32 v3, 26, v3
	s_addc_u32 s41, s10, 0
	s_ashr_i32 s9, s8, 31
	v_add_u32_e32 v8, v4, v3
	s_lshl_b64 s[10:11], s[8:9], 19
	v_ashrrev_i32_e32 v3, 6, v8
	v_and_b32_e32 v8, 0xc0, v8
	s_add_u32 s28, s80, s10
	v_sub_u32_e32 v4, v4, v8
	s_addc_u32 s29, s81, s11
	s_ashr_i32 s27, s26, 31
	v_lshlrev_b32_e32 v9, 5, v2
	v_ashrrev_i16_sdwa v4, v226, sext(v4) dst_sel:DWORD dst_unused:UNUSED_PAD src0_sel:DWORD src1_sel:BYTE_0
	s_lshl_b64 s[10:11], s[26:27], 19
	v_and_b32_e32 v9, 32, v9
	v_bfe_i32 v4, v4, 0, 16
	s_add_u32 s30, s40, s10
	v_add_u32_e32 v7, v3, v7
	v_and_b32_e32 v11, 3, v3
	s_mov_b32 s10, 0x1fffe0
	v_add_lshl_u32 v9, v9, v4, 1
	v_lshlrev_b32_e32 v8, 1, v7
	v_lshrrev_b32_e32 v10, 2, v7
	v_and_or_b32 v11, v7, s10, v11
	v_lshl_add_u32 v130, v7, 11, v9
	v_add_u32_e32 v7, 0x2000, v6
	v_ashrrev_i32_e32 v6, 31, v7
	v_lshrrev_b32_e32 v6, 22, v6
	v_and_b32_e32 v8, 24, v8
	v_and_b32_e32 v10, 4, v10
	v_add_u32_e32 v6, v7, v6
	v_or3_b32 v8, v11, v10, v8
	v_ashrrev_i32_e32 v6, 10, v6
	v_lshl_add_u32 v132, v8, 11, v9
	v_mul_i32_i24_e32 v8, 0x400, v6
	v_sub_u32_e32 v7, v7, v8
	v_lshrrev_b32_e32 v8, 4, v7
	v_bitop3_b32 v8, v8, v7, 32 bitop3:0x6c
	v_lshlrev_b32_e32 v7, 3, v6
	v_and_b32_e32 v9, -16, v7
	v_ashrrev_i32_e32 v7, 31, v8
	v_lshrrev_b32_e32 v7, 26, v7
	v_add_u32_e32 v10, v8, v7
	s_addc_u32 s31, s41, s11
	s_ashr_i32 s9, s14, 6
	v_ashrrev_i32_e32 v7, 6, v10
	v_and_b32_e32 v10, 0xc0, v10
	v_add_u32_e32 v9, v7, v9
	v_sub_u32_e32 v8, v8, v10
	s_lshl_b32 s27, s9, 10
	v_lshlrev_b32_e32 v11, 5, v6
	v_ashrrev_i16_sdwa v8, v226, sext(v8) dst_sel:DWORD dst_unused:UNUSED_PAD src0_sel:DWORD src1_sel:BYTE_0
	v_lshlrev_b32_e32 v10, 1, v9
	v_lshrrev_b32_e32 v12, 2, v9
	v_and_b32_e32 v13, 3, v7
	s_add_i32 s44, s27, 0
	v_and_b32_e32 v11, 32, v11
	v_bfe_i32 v8, v8, 0, 16
	v_and_b32_e32 v10, 24, v10
	v_and_b32_e32 v12, 4, v12
	v_and_or_b32 v13, v9, s10, v13
	s_add_i32 m0, s44, 0x10000
	v_or3_b32 v10, v13, v12, v10
	v_add_lshl_u32 v11, v11, v8, 1
	s_ashr_i32 s16, s14, 8
	global_load_lds_dwordx4 v132, s[30:31]
	s_add_i32 m0, s44, 0x12000
	v_lshl_add_u32 v136, v10, 11, v11
	s_add_u32 s10, s30, 0x40000
	global_load_lds_dwordx4 v136, s[30:31]
	s_addc_u32 s11, s31, 0
	s_add_i32 m0, s44, 0x14000
	s_add_i32 s45, s44, 0x2000
	global_load_lds_dwordx4 v132, s[10:11]
	s_add_i32 m0, s44, 0x16000
	v_lshl_add_u32 v134, v9, 11, v11
	global_load_lds_dwordx4 v136, s[10:11]
	s_mov_b32 m0, s44
	s_add_u32 s10, s28, 0x40000
	global_load_lds_dwordx4 v130, s[28:29]
	s_mov_b32 m0, s45
	s_addc_u32 s11, s29, 0
	s_add_i32 s43, s44, 0x4000
	global_load_lds_dwordx4 v134, s[28:29]
	s_mov_b32 m0, s43
	s_add_i32 s46, s44, 0x6000
	global_load_lds_dwordx4 v130, s[10:11]
	s_mov_b32 m0, s46
	s_cmp_eq_u32 s16, 1
	global_load_lds_dwordx4 v134, s[10:11]
	s_cselect_b64 s[10:11], -1, 0
	s_cmp_lg_u32 s16, 1
	s_cbranch_scc1 .LBB0_280
	s_setprio 1
	s_barrier

.LBB0_288:
	s_add_u32 s30, s28, 0xfffc0080
	s_addc_u32 s31, s29, -1
	s_add_i32 s56, 0, 0x10000
	s_cmp_eq_u32 s55, 12
	s_cselect_b32 s35, s21, s31
	s_cselect_b32 s34, s36, s30
	s_cselect_b32 s31, s19, s39
	s_cselect_b32 s30, s37, s38
	s_add_i32 s58, 0, 0x14000
	v_add_u32_e32 v166, s56, v147
	v_add_u32_e32 v182, s58, v147
	ds_read_b128 v[142:145], v166
	ds_read_b128 v[158:161], v166 offset:1024
	ds_read_b128 v[162:165], v166 offset:2048
	ds_read_b128 v[166:169], v166 offset:3072
	ds_read_b128 v[170:173], v182
	ds_read_b128 v[174:177], v182 offset:1024
	ds_read_b128 v[178:181], v182 offset:2048
	ds_read_b128 v[182:185], v182 offset:3072
	v_lshl_add_u64 v[224:225], s[28:29], 0, v[140:141]
	s_add_i32 m0, s44, 0xc000
	ds_read_b128 v[186:189], v157
	ds_read_b128 v[190:193], v157 offset:1024
	ds_read_b128 v[194:197], v157 offset:2048
	ds_read_b128 v[198:201], v157 offset:3072
	ds_read_b128 v[202:205], v157 offset:4096
	ds_read_b128 v[206:209], v157 offset:5120
	ds_read_b128 v[220:223], v157 offset:6144
	ds_read_b128 v[236:239], v157 offset:7168
	global_load_lds_dwordx4 v[224:225], off
	v_lshl_add_u64 v[224:225], s[28:29], 0, v[138:139]
	s_add_i32 m0, s44, 0xe000
	s_nop 0
	global_load_lds_dwordx4 v[224:225], off
	s_waitcnt vmcnt(8)
	s_waitcnt lgkmcnt(0)
	s_barrier
	s_waitcnt lgkmcnt(0)
	v_mfma_f32_16x16x32_bf16 v[126:129], v[142:145], v[186:189], v[126:129]
	v_mfma_f32_16x16x32_bf16 v[122:125], v[162:165], v[186:189], v[122:125]
	v_mfma_f32_16x16x32_bf16 v[110:113], v[142:145], v[194:197], v[110:113]
	v_mfma_f32_16x16x32_bf16 v[106:109], v[162:165], v[194:197], v[106:109]
	v_mfma_f32_16x16x32_bf16 v[94:97], v[142:145], v[202:205], v[94:97]
	v_mfma_f32_16x16x32_bf16 v[90:93], v[162:165], v[202:205], v[90:93]
	v_mfma_f32_16x16x32_bf16 v[78:81], v[142:145], v[220:223], v[78:81]
	v_mfma_f32_16x16x32_bf16 v[74:77], v[162:165], v[220:223], v[74:77]
	v_mfma_f32_16x16x32_bf16 v[126:129], v[158:161], v[190:193], v[126:129]
	v_mfma_f32_16x16x32_bf16 v[122:125], v[166:169], v[190:193], v[122:125]
	v_mfma_f32_16x16x32_bf16 v[110:113], v[158:161], v[198:201], v[110:113]
	v_mfma_f32_16x16x32_bf16 v[106:109], v[166:169], v[198:201], v[106:109]
	v_mfma_f32_16x16x32_bf16 v[94:97], v[158:161], v[206:209], v[94:97]
	v_mfma_f32_16x16x32_bf16 v[90:93], v[166:169], v[206:209], v[90:93]
	v_mfma_f32_16x16x32_bf16 v[78:81], v[158:161], v[236:239], v[78:81]
	v_mfma_f32_16x16x32_bf16 v[74:77], v[166:169], v[236:239], v[74:77]
	v_mfma_f32_16x16x32_bf16 v[118:121], v[170:173], v[186:189], v[118:121]
	v_mfma_f32_16x16x32_bf16 v[114:117], v[178:181], v[186:189], v[114:117]
	v_mfma_f32_16x16x32_bf16 v[102:105], v[170:173], v[194:197], v[102:105]
	v_mfma_f32_16x16x32_bf16 v[98:101], v[178:181], v[194:197], v[98:101]
	v_mfma_f32_16x16x32_bf16 v[86:89], v[170:173], v[202:205], v[86:89]
	v_mfma_f32_16x16x32_bf16 v[82:85], v[178:181], v[202:205], v[82:85]
	v_mfma_f32_16x16x32_bf16 v[70:73], v[170:173], v[220:223], v[70:73]
	v_mfma_f32_16x16x32_bf16 v[66:69], v[178:181], v[220:223], v[66:69]
	v_mfma_f32_16x16x32_bf16 v[118:121], v[174:177], v[190:193], v[118:121]
	v_mfma_f32_16x16x32_bf16 v[114:117], v[182:185], v[190:193], v[114:117]
	v_mfma_f32_16x16x32_bf16 v[102:105], v[174:177], v[198:201], v[102:105]
	v_mfma_f32_16x16x32_bf16 v[98:101], v[182:185], v[198:201], v[98:101]
	v_mfma_f32_16x16x32_bf16 v[86:89], v[174:177], v[206:209], v[86:89]
	v_mfma_f32_16x16x32_bf16 v[82:85], v[182:185], v[206:209], v[82:85]
	v_mfma_f32_16x16x32_bf16 v[70:73], v[174:177], v[236:239], v[70:73]
	v_mfma_f32_16x16x32_bf16 v[66:69], v[182:185], v[236:239], v[66:69]
	s_barrier
	s_add_i32 s56, s56, s27
	v_lshl_add_u64 v[224:225], s[30:31], 0, v[132:133]
	s_mov_b32 m0, s56
	ds_read_b128 v[186:189], v157 offset:16384
	ds_read_b128 v[190:193], v157 offset:17408
	ds_read_b128 v[194:197], v157 offset:18432
	ds_read_b128 v[198:201], v157 offset:19456
	ds_read_b128 v[202:205], v157 offset:20480
	ds_read_b128 v[206:209], v157 offset:21504
	ds_read_b128 v[220:223], v157 offset:22528
	ds_read_b128 v[236:239], v157 offset:23552
	global_load_lds_dwordx4 v[224:225], off
	s_add_i32 m0, s56, 0x2000
	s_add_u32 s56, s30, 0x40000
	v_lshl_add_u64 v[230:231], s[30:31], 0, v[136:137]
	s_addc_u32 s57, s31, 0
	s_add_i32 s58, s58, s27
	global_load_lds_dwordx4 v[230:231], off
	v_lshl_add_u64 v[240:241], s[56:57], 0, v[132:133]
	s_mov_b32 m0, s58
	v_lshl_add_u64 v[242:243], s[34:35], 0, v[134:135]
	global_load_lds_dwordx4 v[240:241], off
	v_lshl_add_u64 v[240:241], s[56:57], 0, v[136:137]
	s_add_i32 m0, s58, 0x2000
	s_nop 0
	global_load_lds_dwordx4 v[240:241], off
	v_lshl_add_u64 v[240:241], s[34:35], 0, v[130:131]
	s_mov_b32 m0, s44
	s_nop 0
	global_load_lds_dwordx4 v[240:241], off
	s_mov_b32 m0, s45
	s_nop 0
	global_load_lds_dwordx4 v[242:243], off
	s_waitcnt vmcnt(8)
	s_waitcnt lgkmcnt(0)
	s_barrier
	s_waitcnt lgkmcnt(0)
	v_mfma_f32_16x16x32_bf16 v[62:65], v[142:145], v[186:189], v[62:65]
	v_mfma_f32_16x16x32_bf16 v[58:61], v[162:165], v[186:189], v[58:61]
	v_mfma_f32_16x16x32_bf16 v[46:49], v[142:145], v[194:197], v[46:49]
	v_mfma_f32_16x16x32_bf16 v[42:45], v[162:165], v[194:197], v[42:45]
	v_mfma_f32_16x16x32_bf16 v[30:33], v[142:145], v[202:205], v[30:33]
	v_mfma_f32_16x16x32_bf16 v[26:29], v[162:165], v[202:205], v[26:29]
	v_mfma_f32_16x16x32_bf16 v[14:17], v[142:145], v[220:223], v[14:17]
	v_mfma_f32_16x16x32_bf16 v[10:13], v[162:165], v[220:223], v[10:13]
	v_mfma_f32_16x16x32_bf16 v[62:65], v[158:161], v[190:193], v[62:65]
	v_mfma_f32_16x16x32_bf16 v[58:61], v[166:169], v[190:193], v[58:61]
	v_mfma_f32_16x16x32_bf16 v[46:49], v[158:161], v[198:201], v[46:49]
	v_mfma_f32_16x16x32_bf16 v[42:45], v[166:169], v[198:201], v[42:45]
	v_mfma_f32_16x16x32_bf16 v[30:33], v[158:161], v[206:209], v[30:33]
	v_mfma_f32_16x16x32_bf16 v[26:29], v[166:169], v[206:209], v[26:29]
	v_mfma_f32_16x16x32_bf16 v[14:17], v[158:161], v[236:239], v[14:17]
	v_mfma_f32_16x16x32_bf16 v[10:13], v[166:169], v[236:239], v[10:13]
	v_mfma_f32_16x16x32_bf16 v[54:57], v[170:173], v[186:189], v[54:57]
	v_mfma_f32_16x16x32_bf16 v[50:53], v[178:181], v[186:189], v[50:53]
	v_mfma_f32_16x16x32_bf16 v[38:41], v[170:173], v[194:197], v[38:41]
	v_mfma_f32_16x16x32_bf16 v[34:37], v[178:181], v[194:197], v[34:37]
	v_mfma_f32_16x16x32_bf16 v[22:25], v[170:173], v[202:205], v[22:25]
	v_mfma_f32_16x16x32_bf16 v[18:21], v[178:181], v[202:205], v[18:21]
	v_mfma_f32_16x16x32_bf16 v[6:9], v[170:173], v[220:223], v[6:9]
	v_mfma_f32_16x16x32_bf16 v[2:5], v[178:181], v[220:223], v[2:5]
	v_mfma_f32_16x16x32_bf16 v[54:57], v[174:177], v[190:193], v[54:57]
	v_mfma_f32_16x16x32_bf16 v[50:53], v[182:185], v[190:193], v[50:53]
	v_mfma_f32_16x16x32_bf16 v[38:41], v[174:177], v[198:201], v[38:41]
	v_mfma_f32_16x16x32_bf16 v[34:37], v[182:185], v[198:201], v[34:37]
	v_mfma_f32_16x16x32_bf16 v[22:25], v[174:177], v[206:209], v[22:25]
	v_mfma_f32_16x16x32_bf16 v[18:21], v[182:185], v[206:209], v[18:21]
	v_mfma_f32_16x16x32_bf16 v[6:9], v[174:177], v[236:239], v[6:9]
	v_mfma_f32_16x16x32_bf16 v[2:5], v[182:185], v[236:239], v[2:5]
	s_barrier
	s_add_i32 s56, 0, 0x18000
	s_add_i32 s57, 0, 0x1c000
	v_add_u32_e32 v166, s56, v147
	v_add_u32_e32 v182, s57, v147
	ds_read_b128 v[142:145], v166
	ds_read_b128 v[158:161], v166 offset:1024
	ds_read_b128 v[162:165], v166 offset:2048
	ds_read_b128 v[166:169], v166 offset:3072
	ds_read_b128 v[170:173], v182
	ds_read_b128 v[174:177], v182 offset:1024
	ds_read_b128 v[178:181], v182 offset:2048
	ds_read_b128 v[182:185], v182 offset:3072
	s_add_u32 s34, s34, 0x40000
	s_addc_u32 s35, s35, 0
	s_mov_b32 m0, s43
	v_lshl_add_u64 v[244:245], s[34:35], 0, v[130:131]
	ds_read_b128 v[186:189], v157 offset:32768
	ds_read_b128 v[190:193], v157 offset:33792
	ds_read_b128 v[194:197], v157 offset:34816
	ds_read_b128 v[198:201], v157 offset:35840
	ds_read_b128 v[202:205], v157 offset:36864
	ds_read_b128 v[206:209], v157 offset:37888
	ds_read_b128 v[220:223], v157 offset:38912
	ds_read_b128 v[236:239], v157 offset:39936
	global_load_lds_dwordx4 v[244:245], off
	v_lshl_add_u64 v[244:245], s[34:35], 0, v[134:135]
	s_mov_b32 m0, s46
	s_nop 0
	global_load_lds_dwordx4 v[244:245], off
	s_waitcnt vmcnt(8)
	s_waitcnt lgkmcnt(0)
	s_barrier
	s_waitcnt lgkmcnt(0)
	v_mfma_f32_16x16x32_bf16 v[126:129], v[142:145], v[186:189], v[126:129]
	v_mfma_f32_16x16x32_bf16 v[122:125], v[162:165], v[186:189], v[122:125]
	v_mfma_f32_16x16x32_bf16 v[110:113], v[142:145], v[194:197], v[110:113]
	v_mfma_f32_16x16x32_bf16 v[106:109], v[162:165], v[194:197], v[106:109]
	v_mfma_f32_16x16x32_bf16 v[94:97], v[142:145], v[202:205], v[94:97]
	v_mfma_f32_16x16x32_bf16 v[90:93], v[162:165], v[202:205], v[90:93]
	v_mfma_f32_16x16x32_bf16 v[78:81], v[142:145], v[220:223], v[78:81]
	v_mfma_f32_16x16x32_bf16 v[74:77], v[162:165], v[220:223], v[74:77]
	v_mfma_f32_16x16x32_bf16 v[126:129], v[158:161], v[190:193], v[126:129]
	v_mfma_f32_16x16x32_bf16 v[122:125], v[166:169], v[190:193], v[122:125]
	v_mfma_f32_16x16x32_bf16 v[110:113], v[158:161], v[198:201], v[110:113]
	v_mfma_f32_16x16x32_bf16 v[106:109], v[166:169], v[198:201], v[106:109]
	v_mfma_f32_16x16x32_bf16 v[94:97], v[158:161], v[206:209], v[94:97]
	v_mfma_f32_16x16x32_bf16 v[90:93], v[166:169], v[206:209], v[90:93]
	v_mfma_f32_16x16x32_bf16 v[78:81], v[158:161], v[236:239], v[78:81]
	v_mfma_f32_16x16x32_bf16 v[74:77], v[166:169], v[236:239], v[74:77]
	v_mfma_f32_16x16x32_bf16 v[118:121], v[170:173], v[186:189], v[118:121]
	v_mfma_f32_16x16x32_bf16 v[114:117], v[178:181], v[186:189], v[114:117]
	v_mfma_f32_16x16x32_bf16 v[102:105], v[170:173], v[194:197], v[102:105]
	v_mfma_f32_16x16x32_bf16 v[98:101], v[178:181], v[194:197], v[98:101]
	v_mfma_f32_16x16x32_bf16 v[86:89], v[170:173], v[202:205], v[86:89]
	v_mfma_f32_16x16x32_bf16 v[82:85], v[178:181], v[202:205], v[82:85]
	v_mfma_f32_16x16x32_bf16 v[70:73], v[170:173], v[220:223], v[70:73]
	v_mfma_f32_16x16x32_bf16 v[66:69], v[178:181], v[220:223], v[66:69]
	v_mfma_f32_16x16x32_bf16 v[118:121], v[174:177], v[190:193], v[118:121]
	v_mfma_f32_16x16x32_bf16 v[114:117], v[182:185], v[190:193], v[114:117]
	v_mfma_f32_16x16x32_bf16 v[102:105], v[174:177], v[198:201], v[102:105]
	v_mfma_f32_16x16x32_bf16 v[98:101], v[182:185], v[198:201], v[98:101]
	v_mfma_f32_16x16x32_bf16 v[86:89], v[174:177], v[206:209], v[86:89]
	v_mfma_f32_16x16x32_bf16 v[82:85], v[182:185], v[206:209], v[82:85]
	v_mfma_f32_16x16x32_bf16 v[70:73], v[174:177], v[236:239], v[70:73]
	v_mfma_f32_16x16x32_bf16 v[66:69], v[182:185], v[236:239], v[66:69]
	s_barrier
	s_add_i32 s34, s56, s27
	v_lshl_add_u64 v[224:225], v[224:225], 0, s[96:97]
	s_mov_b32 m0, s34
	ds_read_b128 v[186:189], v157 offset:49152
	ds_read_b128 v[190:193], v157 offset:50176
	ds_read_b128 v[194:197], v157 offset:51200
	ds_read_b128 v[198:201], v157 offset:52224
	ds_read_b128 v[202:205], v157 offset:53248
	ds_read_b128 v[206:209], v157 offset:54272
	ds_read_b128 v[220:223], v157 offset:55296
	ds_read_b128 v[236:239], v157 offset:56320
	global_load_lds_dwordx4 v[224:225], off
	s_add_i32 m0, s34, 0x2000
	s_add_u32 s30, s30, 0x40080
	v_lshl_add_u64 v[224:225], v[230:231], 0, s[96:97]
	s_addc_u32 s31, s31, 0
	s_add_i32 s34, s57, s27
	global_load_lds_dwordx4 v[224:225], off
	v_lshl_add_u64 v[224:225], s[30:31], 0, v[132:133]
	s_mov_b32 m0, s34
	s_nop 0
	global_load_lds_dwordx4 v[224:225], off
	v_lshl_add_u64 v[224:225], s[30:31], 0, v[136:137]
	s_add_i32 m0, s34, 0x2000
	s_nop 0
	global_load_lds_dwordx4 v[224:225], off
	v_lshl_add_u64 v[224:225], v[240:241], 0, s[96:97]
	s_mov_b32 m0, s47
	s_nop 0
	global_load_lds_dwordx4 v[224:225], off
	v_lshl_add_u64 v[224:225], v[242:243], 0, s[96:97]
	s_mov_b32 m0, s48
	s_nop 0
	global_load_lds_dwordx4 v[224:225], off
	s_waitcnt vmcnt(8)
	s_waitcnt lgkmcnt(0)
	s_barrier
	s_waitcnt lgkmcnt(0)
	v_mfma_f32_16x16x32_bf16 v[62:65], v[142:145], v[186:189], v[62:65]
	v_mfma_f32_16x16x32_bf16 v[58:61], v[162:165], v[186:189], v[58:61]
	v_mfma_f32_16x16x32_bf16 v[46:49], v[142:145], v[194:197], v[46:49]
	v_mfma_f32_16x16x32_bf16 v[42:45], v[162:165], v[194:197], v[42:45]
	v_mfma_f32_16x16x32_bf16 v[30:33], v[142:145], v[202:205], v[30:33]
	v_mfma_f32_16x16x32_bf16 v[26:29], v[162:165], v[202:205], v[26:29]
	v_mfma_f32_16x16x32_bf16 v[14:17], v[142:145], v[220:223], v[14:17]
	v_mfma_f32_16x16x32_bf16 v[10:13], v[162:165], v[220:223], v[10:13]
	v_mfma_f32_16x16x32_bf16 v[62:65], v[158:161], v[190:193], v[62:65]
	v_mfma_f32_16x16x32_bf16 v[58:61], v[166:169], v[190:193], v[58:61]
	v_mfma_f32_16x16x32_bf16 v[46:49], v[158:161], v[198:201], v[46:49]
	v_mfma_f32_16x16x32_bf16 v[42:45], v[166:169], v[198:201], v[42:45]
	v_mfma_f32_16x16x32_bf16 v[30:33], v[158:161], v[206:209], v[30:33]
	v_mfma_f32_16x16x32_bf16 v[26:29], v[166:169], v[206:209], v[26:29]
	v_mfma_f32_16x16x32_bf16 v[14:17], v[158:161], v[236:239], v[14:17]
	v_mfma_f32_16x16x32_bf16 v[10:13], v[166:169], v[236:239], v[10:13]
	v_mfma_f32_16x16x32_bf16 v[54:57], v[170:173], v[186:189], v[54:57]
	v_mfma_f32_16x16x32_bf16 v[50:53], v[178:181], v[186:189], v[50:53]
	v_mfma_f32_16x16x32_bf16 v[38:41], v[170:173], v[194:197], v[38:41]
	v_mfma_f32_16x16x32_bf16 v[34:37], v[178:181], v[194:197], v[34:37]
	v_mfma_f32_16x16x32_bf16 v[22:25], v[170:173], v[202:205], v[22:25]
	v_mfma_f32_16x16x32_bf16 v[18:21], v[178:181], v[202:205], v[18:21]
	v_mfma_f32_16x16x32_bf16 v[6:9], v[170:173], v[220:223], v[6:9]
	v_mfma_f32_16x16x32_bf16 v[2:5], v[178:181], v[220:223], v[2:5]
	v_mfma_f32_16x16x32_bf16 v[54:57], v[174:177], v[190:193], v[54:57]
	v_mfma_f32_16x16x32_bf16 v[50:53], v[182:185], v[190:193], v[50:53]
	v_mfma_f32_16x16x32_bf16 v[38:41], v[174:177], v[198:201], v[38:41]
	v_mfma_f32_16x16x32_bf16 v[34:37], v[182:185], v[198:201], v[34:37]
	v_mfma_f32_16x16x32_bf16 v[22:25], v[174:177], v[206:209], v[22:25]
	v_mfma_f32_16x16x32_bf16 v[18:21], v[182:185], v[206:209], v[18:21]
	v_mfma_f32_16x16x32_bf16 v[6:9], v[174:177], v[236:239], v[6:9]
	v_mfma_f32_16x16x32_bf16 v[2:5], v[182:185], v[236:239], v[2:5]
	s_barrier
	s_add_i32 s55, s55, 2
	s_add_u32 s38, s38, 0x100
	s_addc_u32 s39, s39, 0
	s_add_u32 s28, s28, 0x100
	s_addc_u32 s29, s29, 0
	s_cmp_gt_u32 s55, 13
	s_cbranch_scc0 .LBB0_288
	s_and_b64 vcc, exec, s[12:13]
	s_cbranch_vccz .LBB0_291
	s_barrier

.LBB0_354:
	v_readlane_b32 s6, v254, 47
	s_cmpk_gt_i32 s6, 0x57f
	v_readfirstlane_b32 s16, v234
	v_readlane_b32 s7, v254, 48
	s_cbranch_scc1 .LBB0_386
	v_lshlrev_b32_e32 v2, 4, v234
	v_add_u32_e32 v3, 0x2000, v2
	v_ashrrev_i32_e32 v4, 31, v3
	v_lshrrev_b32_e32 v4, 22, v4
	v_add_u32_e32 v4, v3, v4
	v_ashrrev_i32_e32 v10, 10, v4
	v_mul_i32_i24_e32 v4, 0x400, v10
	v_sub_u32_e32 v3, v3, v4
	v_lshrrev_b32_e32 v4, 4, v3
	v_bitop3_b32 v3, v4, v3, 32 bitop3:0x6c
	s_ashr_i32 s17, s16, 6
	v_ashrrev_i32_e32 v4, 31, v3
	s_ashr_i32 s18, s16, 8
	s_lshl_b32 s44, s17, 10
	v_lshrrev_b32_e32 v4, 26, v4
	s_and_b64 s[6:7], s[4:5], exec
	v_add_u32_e32 v4, v3, v4
	v_lshlrev_b32_e32 v5, 3, v10
	s_mov_b32 s6, 0x1900000
	v_ashrrev_i32_e32 v12, 6, v4
	v_and_b32_e32 v5, -16, v5
	s_cselect_b32 s6, s6, 0x5180000
	v_add_u32_e32 v5, v12, v5
	s_add_u32 s45, s0, s6
	v_and_b32_e32 v6, 3, v12
	s_mov_b32 s6, 0x1fffe0
	v_lshrrev_b32_e32 v7, 2, v5
	v_lshlrev_b32_e32 v8, 1, v5
	v_and_b32_e32 v4, 0xc0, v4
	v_and_or_b32 v6, v5, s6, v6
	v_and_b32_e32 v7, 4, v7
	v_and_b32_e32 v8, 24, v8
	v_sub_u32_e32 v3, v3, v4
	v_or3_b32 v6, v6, v7, v8
	v_lshlrev_b32_e32 v7, 5, v10
	v_ashrrev_i16_sdwa v3, v226, sext(v3) dst_sel:DWORD dst_unused:UNUSED_PAD src0_sel:DWORD src1_sel:BYTE_0
	v_and_b32_e32 v7, 32, v7
	v_bfe_i32 v13, v3, 0, 16
	v_add_lshl_u32 v3, v7, v13, 1
	s_waitcnt vmcnt(0)
	v_lshl_add_u32 v130, v6, 11, v3
	v_lshl_add_u32 v132, v5, 11, v3
	v_bfe_i32 v3, v234, 27, 1
	v_lshrrev_b32_e32 v3, 22, v3
	v_add_u32_e32 v3, v2, v3
	v_and_b32_e32 v3, 0xfffffc00, v3
	v_sub_u32_e32 v2, v2, v3
	v_lshrrev_b32_e32 v3, 4, v2
	v_ashrrev_i32_e32 v4, 31, v234
	s_addc_u32 s46, s1, 0
	v_bitop3_b32 v2, v3, v2, 32 bitop3:0x6c
	v_lshrrev_b32_e32 v4, 26, v4
	v_ashrrev_i32_e32 v3, 31, v2
	v_add_u32_e32 v4, v234, v4
	s_and_b64 s[4:5], s[4:5], exec
	v_lshrrev_b32_e32 v3, 26, v3
	v_ashrrev_i32_e32 v15, 6, v4
	s_mov_b32 s4, 0x30000
	v_add_u32_e32 v3, v2, v3
	v_lshlrev_b32_e32 v4, 3, v15
	s_cselect_b32 s4, s4, 0x10000
	v_ashrrev_i32_e32 v14, 6, v3
	v_and_b32_e32 v4, -16, v4
	s_add_u32 s12, s78, s4
	v_readlane_b32 s4, v254, 47
	v_add_u32_e32 v4, v14, v4
	v_and_b32_e32 v5, 3, v14
	s_addc_u32 s13, s79, 0
	s_ashr_i32 s47, s4, 31
	v_and_or_b32 v5, v4, s6, v5
	s_mov_b32 s6, s4
	s_lshr_b32 s4, s47, 29
	v_readlane_b32 s5, v254, 48
	s_add_i32 s4, s6, s4
	s_ashr_i32 s5, s4, 3
	s_and_b32 s4, s4, -8
	s_sub_i32 s4, s6, s4
	s_cmp_lt_i32 s4, 0
	s_movk_i32 s6, 0xb1
	s_cselect_b32 s6, s6, 0xb0
	s_mul_i32 s4, s4, s6
	s_add_i32 s4, s4, s5
	s_mul_hi_i32 s5, s4, 0x2e8ba2e9
	s_lshr_b32 s6, s5, 31
	s_ashr_i32 s5, s5, 5
	s_add_i32 s5, s5, s6
	s_lshl_b32 s6, s5, 3
	s_mulk_i32 s5, 0xb0
	s_sub_i32 s5, s4, s5
	s_bfe_u32 s4, s5, 0x3001c
	s_add_i32 s7, s5, s4
	s_sext_i32_i16 s4, s7
	s_and_b32 s7, s7, 0xfff8
	s_sub_i32 s5, s5, s7
	s_sext_i32_i16 s5, s5
	v_lshrrev_b32_e32 v6, 2, v4
	v_lshlrev_b32_e32 v7, 1, v4
	v_and_b32_e32 v3, 0xc0, v3
	s_lshr_b32 s4, s4, 3
	s_add_i32 s28, s6, s5
	v_and_b32_e32 v6, 4, v6
	v_and_b32_e32 v7, 24, v7
	v_sub_u32_e32 v2, v2, v3
	s_ashr_i32 s29, s28, 31
	s_bfe_i64 s[14:15], s[4:5], 0x100000
	v_or3_b32 v5, v5, v6, v7
	v_lshlrev_b32_e32 v6, 5, v15
	v_ashrrev_i16_sdwa v2, v226, sext(v2) dst_sel:DWORD dst_unused:UNUSED_PAD src0_sel:DWORD src1_sel:BYTE_0
	s_lshl_b64 s[6:7], s[28:29], 19
	s_lshl_b64 s[14:15], s[14:15], 19
	v_and_b32_e32 v11, 15, v233
	v_and_b32_e32 v6, 32, v6
	v_bfe_i32 v16, v2, 0, 16
	s_add_u32 s30, s45, s14
	v_lshl_or_b32 v1, s18, 6, v11
	v_add_lshl_u32 v2, v6, v16, 1
	s_addc_u32 s31, s46, s15
	s_lshl_b32 s5, s28, 8
	v_lshl_add_u32 v134, v5, 11, v2
	v_lshl_add_u32 v136, v4, 11, v2
	v_add_u32_e32 v2, s5, v1
	v_ashrrev_i32_e32 v3, 31, v2
	v_lshl_add_u64 v[2:3], v[2:3], 2, s[12:13]
	v_or_b32_e32 v148, 16, v1
	global_load_dword v166, v[2:3], off
	v_add_u32_e32 v2, s5, v148
	v_ashrrev_i32_e32 v3, 31, v2
	v_lshl_add_u64 v[2:3], v[2:3], 2, s[12:13]
	v_or_b32_e32 v149, 32, v1
	global_load_dword v165, v[2:3], off
	v_add_u32_e32 v2, s5, v149
	v_ashrrev_i32_e32 v3, 31, v2
	v_lshl_add_u64 v[2:3], v[2:3], 2, s[12:13]
	v_or_b32_e32 v150, 48, v1
	global_load_dword v163, v[2:3], off
	v_add_u32_e32 v2, s5, v150
	v_ashrrev_i32_e32 v3, 31, v2
	v_lshl_add_u64 v[2:3], v[2:3], 2, s[12:13]
	v_add_u32_e32 v151, 0x80, v1
	global_load_dword v162, v[2:3], off
	v_add_u32_e32 v2, s5, v151
	v_ashrrev_i32_e32 v3, 31, v2
	s_add_i32 s48, s44, 0
	v_lshl_add_u64 v[2:3], v[2:3], 2, s[12:13]
	v_add_u32_e32 v152, 0x90, v1
	s_add_i32 m0, s48, 0x10000
	global_load_dword v161, v[2:3], off
	v_add_u32_e32 v2, s5, v152
	global_load_lds_dwordx4 v134, s[30:31]
	s_add_i32 m0, s48, 0x12000
	v_ashrrev_i32_e32 v3, 31, v2
	s_add_u32 s14, s30, 0x40000
	v_lshl_add_u64 v[2:3], v[2:3], 2, s[12:13]
	v_add_u32_e32 v153, 0xa0, v1
	global_load_lds_dwordx4 v130, s[30:31]
	s_addc_u32 s15, s31, 0
	s_add_i32 m0, s48, 0x14000
	global_load_dword v160, v[2:3], off
	v_add_u32_e32 v2, s5, v153
	global_load_lds_dwordx4 v134, s[14:15]
	s_add_i32 m0, s48, 0x16000
	v_ashrrev_i32_e32 v3, 31, v2
	s_add_u32 s34, s80, s6
	v_lshl_add_u64 v[2:3], v[2:3], 2, s[12:13]
	v_add_u32_e32 v154, 0xb0, v1
	s_addc_u32 s35, s81, s7
	s_add_i32 s49, s48, 0x2000
	global_load_dword v159, v[2:3], off
	v_add_u32_e32 v2, s5, v154
	global_load_lds_dwordx4 v130, s[14:15]
	s_mov_b32 m0, s48
	s_add_u32 s6, s34, 0x40000
	v_ashrrev_i32_e32 v3, 31, v2
	global_load_lds_dwordx4 v136, s[34:35]
	s_mov_b32 m0, s49
	s_addc_u32 s7, s35, 0
	s_add_i32 s50, s48, 0x4000
	v_lshl_add_u64 v[2:3], v[2:3], 2, s[12:13]
	global_load_lds_dwordx4 v132, s[34:35]
	s_mov_b32 m0, s50
	s_add_i32 s51, s48, 0x6000
	global_load_dword v158, v[2:3], off
	v_mov_b32_e32 v135, v0
	global_load_lds_dwordx4 v136, s[6:7]
	s_mov_b32 m0, s51
	v_mov_b32_e32 v131, v0
	global_load_lds_dwordx4 v132, s[6:7]
	v_mov_b32_e32 v137, v0
	v_mov_b32_e32 v133, v0
	s_cmp_eq_u32 s18, 1
	v_lshl_add_u64 v[2:3], s[30:31], 0, v[134:135]
	v_lshl_add_u64 v[4:5], s[30:31], 0, v[130:131]
	v_lshl_add_u64 v[6:7], s[34:35], 0, v[136:137]
	v_lshl_add_u64 v[8:9], s[34:35], 0, v[132:133]
	s_cselect_b64 s[14:15], -1, 0
	s_cmp_lg_u32 s18, 1
	s_cbranch_scc1 .LBB0_357
	s_setprio 1
	s_barrier

.LBB0_363:
	s_add_u32 s34, s30, 0xfffc0080
	s_addc_u32 s35, s31, -1
	s_add_i32 s57, 0, 0x10000
	s_cmp_eq_u32 s56, 12
	s_cselect_b32 s37, s23, s35
	s_cselect_b32 s36, s39, s34
	v_add_u32_e32 v146, s57, v155
	s_cselect_b32 s35, s21, s43
	s_cselect_b32 s34, s40, s41
	s_add_i32 s60, 0, 0x14000
	ds_read_b128 v[142:145], v146
	ds_read_b128 v[168:171], v146 offset:1024
	ds_read_b128 v[172:175], v146 offset:2048
	ds_read_b128 v[176:179], v146 offset:3072
	v_add_u32_e32 v146, s60, v155
	ds_read_b128 v[180:183], v146
	ds_read_b128 v[184:187], v146 offset:1024
	ds_read_b128 v[188:191], v146 offset:2048
	ds_read_b128 v[192:195], v146 offset:3072
	v_lshl_add_u64 v[146:147], s[30:31], 0, v[140:141]
	s_add_i32 m0, s48, 0xc000
	ds_read_b128 v[196:199], v157
	ds_read_b128 v[200:203], v157 offset:1024
	ds_read_b128 v[204:207], v157 offset:2048
	ds_read_b128 v[220:223], v157 offset:3072
	ds_read_b128 v[236:239], v157 offset:4096
	ds_read_b128 v[240:243], v157 offset:5120
	ds_read_b128 v[244:247], v157 offset:6144
	ds_read_b128 v[248:251], v157 offset:7168
	global_load_lds_dwordx4 v[146:147], off
	v_lshl_add_u64 v[146:147], s[30:31], 0, v[138:139]
	s_add_i32 m0, s48, 0xe000
	s_nop 0
	global_load_lds_dwordx4 v[146:147], off
	s_waitcnt vmcnt(8)
	s_waitcnt lgkmcnt(0)
	s_barrier
	s_waitcnt lgkmcnt(0)
	v_mfma_f32_16x16x32_bf16 v[126:129], v[142:145], v[196:199], v[126:129]
	v_mfma_f32_16x16x32_bf16 v[118:121], v[172:175], v[196:199], v[118:121]
	v_mfma_f32_16x16x32_bf16 v[110:113], v[142:145], v[204:207], v[110:113]
	v_mfma_f32_16x16x32_bf16 v[102:105], v[172:175], v[204:207], v[102:105]
	v_mfma_f32_16x16x32_bf16 v[94:97], v[142:145], v[236:239], v[94:97]
	v_mfma_f32_16x16x32_bf16 v[86:89], v[172:175], v[236:239], v[86:89]
	v_mfma_f32_16x16x32_bf16 v[78:81], v[142:145], v[244:247], v[78:81]
	v_mfma_f32_16x16x32_bf16 v[70:73], v[172:175], v[244:247], v[70:73]
	v_mfma_f32_16x16x32_bf16 v[126:129], v[168:171], v[200:203], v[126:129]
	v_mfma_f32_16x16x32_bf16 v[118:121], v[176:179], v[200:203], v[118:121]
	v_mfma_f32_16x16x32_bf16 v[110:113], v[168:171], v[220:223], v[110:113]
	v_mfma_f32_16x16x32_bf16 v[102:105], v[176:179], v[220:223], v[102:105]
	v_mfma_f32_16x16x32_bf16 v[94:97], v[168:171], v[240:243], v[94:97]
	v_mfma_f32_16x16x32_bf16 v[86:89], v[176:179], v[240:243], v[86:89]
	v_mfma_f32_16x16x32_bf16 v[78:81], v[168:171], v[248:251], v[78:81]
	v_mfma_f32_16x16x32_bf16 v[70:73], v[176:179], v[248:251], v[70:73]
	v_mfma_f32_16x16x32_bf16 v[122:125], v[180:183], v[196:199], v[122:125]
	v_mfma_f32_16x16x32_bf16 v[114:117], v[188:191], v[196:199], v[114:117]
	v_mfma_f32_16x16x32_bf16 v[106:109], v[180:183], v[204:207], v[106:109]
	v_mfma_f32_16x16x32_bf16 v[98:101], v[188:191], v[204:207], v[98:101]
	v_mfma_f32_16x16x32_bf16 v[90:93], v[180:183], v[236:239], v[90:93]
	v_mfma_f32_16x16x32_bf16 v[82:85], v[188:191], v[236:239], v[82:85]
	v_mfma_f32_16x16x32_bf16 v[74:77], v[180:183], v[244:247], v[74:77]
	v_mfma_f32_16x16x32_bf16 v[66:69], v[188:191], v[244:247], v[66:69]
	v_mfma_f32_16x16x32_bf16 v[122:125], v[184:187], v[200:203], v[122:125]
	v_mfma_f32_16x16x32_bf16 v[114:117], v[192:195], v[200:203], v[114:117]
	v_mfma_f32_16x16x32_bf16 v[106:109], v[184:187], v[220:223], v[106:109]
	v_mfma_f32_16x16x32_bf16 v[98:101], v[192:195], v[220:223], v[98:101]
	v_mfma_f32_16x16x32_bf16 v[90:93], v[184:187], v[240:243], v[90:93]
	v_mfma_f32_16x16x32_bf16 v[82:85], v[192:195], v[240:243], v[82:85]
	v_mfma_f32_16x16x32_bf16 v[74:77], v[184:187], v[248:251], v[74:77]
	v_mfma_f32_16x16x32_bf16 v[66:69], v[192:195], v[248:251], v[66:69]
	s_barrier
	s_add_i32 s57, s57, s44
	v_lshl_add_u64 v[146:147], s[34:35], 0, v[134:135]
	s_mov_b32 m0, s57
	ds_read_b128 v[196:199], v157 offset:16384
	ds_read_b128 v[200:203], v157 offset:17408
	ds_read_b128 v[204:207], v157 offset:18432
	ds_read_b128 v[220:223], v157 offset:19456
	ds_read_b128 v[236:239], v157 offset:20480
	ds_read_b128 v[240:243], v157 offset:21504
	ds_read_b128 v[244:247], v157 offset:22528
	ds_read_b128 v[248:251], v157 offset:23552
	global_load_lds_dwordx4 v[146:147], off
	s_add_i32 m0, s57, 0x2000
	s_add_u32 s58, s34, 0x40000
	v_lshl_add_u64 v[208:209], s[34:35], 0, v[130:131]
	s_addc_u32 s59, s35, 0
	s_add_i32 s57, s60, s44
	global_load_lds_dwordx4 v[208:209], off
	v_lshl_add_u64 v[224:225], s[58:59], 0, v[134:135]
	s_mov_b32 m0, s57
	v_lshl_add_u64 v[230:231], s[36:37], 0, v[132:133]
	global_load_lds_dwordx4 v[224:225], off
	v_lshl_add_u64 v[224:225], s[58:59], 0, v[130:131]
	s_add_i32 m0, s57, 0x2000
	s_nop 0
	global_load_lds_dwordx4 v[224:225], off
	v_lshl_add_u64 v[224:225], s[36:37], 0, v[136:137]
	s_mov_b32 m0, s48
	s_nop 0
	global_load_lds_dwordx4 v[224:225], off
	s_mov_b32 m0, s49
	s_nop 0
	global_load_lds_dwordx4 v[230:231], off
	s_waitcnt vmcnt(8)
	s_waitcnt lgkmcnt(0)
	s_barrier
	s_waitcnt lgkmcnt(0)
	v_mfma_f32_16x16x32_bf16 v[62:65], v[142:145], v[196:199], v[62:65]
	v_mfma_f32_16x16x32_bf16 v[54:57], v[172:175], v[196:199], v[54:57]
	v_mfma_f32_16x16x32_bf16 v[46:49], v[142:145], v[204:207], v[46:49]
	v_mfma_f32_16x16x32_bf16 v[38:41], v[172:175], v[204:207], v[38:41]
	v_mfma_f32_16x16x32_bf16 v[30:33], v[142:145], v[236:239], v[30:33]
	v_mfma_f32_16x16x32_bf16 v[22:25], v[172:175], v[236:239], v[22:25]
	v_mfma_f32_16x16x32_bf16 v[14:17], v[142:145], v[244:247], v[14:17]
	v_mfma_f32_16x16x32_bf16 v[6:9], v[172:175], v[244:247], v[6:9]
	v_mfma_f32_16x16x32_bf16 v[62:65], v[168:171], v[200:203], v[62:65]
	v_mfma_f32_16x16x32_bf16 v[54:57], v[176:179], v[200:203], v[54:57]
	v_mfma_f32_16x16x32_bf16 v[46:49], v[168:171], v[220:223], v[46:49]
	v_mfma_f32_16x16x32_bf16 v[38:41], v[176:179], v[220:223], v[38:41]
	v_mfma_f32_16x16x32_bf16 v[30:33], v[168:171], v[240:243], v[30:33]
	v_mfma_f32_16x16x32_bf16 v[22:25], v[176:179], v[240:243], v[22:25]
	v_mfma_f32_16x16x32_bf16 v[14:17], v[168:171], v[248:251], v[14:17]
	v_mfma_f32_16x16x32_bf16 v[6:9], v[176:179], v[248:251], v[6:9]
	v_mfma_f32_16x16x32_bf16 v[58:61], v[180:183], v[196:199], v[58:61]
	v_mfma_f32_16x16x32_bf16 v[50:53], v[188:191], v[196:199], v[50:53]
	v_mfma_f32_16x16x32_bf16 v[42:45], v[180:183], v[204:207], v[42:45]
	v_mfma_f32_16x16x32_bf16 v[34:37], v[188:191], v[204:207], v[34:37]
	v_mfma_f32_16x16x32_bf16 v[26:29], v[180:183], v[236:239], v[26:29]
	v_mfma_f32_16x16x32_bf16 v[18:21], v[188:191], v[236:239], v[18:21]
	v_mfma_f32_16x16x32_bf16 v[10:13], v[180:183], v[244:247], v[10:13]
	v_mfma_f32_16x16x32_bf16 v[2:5], v[188:191], v[244:247], v[2:5]
	v_mfma_f32_16x16x32_bf16 v[58:61], v[184:187], v[200:203], v[58:61]
	v_mfma_f32_16x16x32_bf16 v[50:53], v[192:195], v[200:203], v[50:53]
	v_mfma_f32_16x16x32_bf16 v[42:45], v[184:187], v[220:223], v[42:45]
	v_mfma_f32_16x16x32_bf16 v[34:37], v[192:195], v[220:223], v[34:37]
	v_mfma_f32_16x16x32_bf16 v[26:29], v[184:187], v[240:243], v[26:29]
	v_mfma_f32_16x16x32_bf16 v[18:21], v[192:195], v[240:243], v[18:21]
	v_mfma_f32_16x16x32_bf16 v[10:13], v[184:187], v[248:251], v[10:13]
	v_mfma_f32_16x16x32_bf16 v[2:5], v[192:195], v[248:251], v[2:5]
	s_barrier
	s_add_i32 s57, 0, 0x18000
	v_add_u32_e32 v164, s57, v155
	s_add_i32 s58, 0, 0x1c000
	ds_read_b128 v[142:145], v164
	ds_read_b128 v[168:171], v164 offset:1024
	ds_read_b128 v[172:175], v164 offset:2048
	ds_read_b128 v[176:179], v164 offset:3072
	v_add_u32_e32 v164, s58, v155
	ds_read_b128 v[180:183], v164
	ds_read_b128 v[184:187], v164 offset:1024
	ds_read_b128 v[188:191], v164 offset:2048
	ds_read_b128 v[192:195], v164 offset:3072
	s_add_u32 s36, s36, 0x40000
	s_addc_u32 s37, s37, 0
	s_mov_b32 m0, s50
	v_lshl_add_u64 v[252:253], s[36:37], 0, v[136:137]
	ds_read_b128 v[196:199], v157 offset:32768
	ds_read_b128 v[200:203], v157 offset:33792
	ds_read_b128 v[204:207], v157 offset:34816
	ds_read_b128 v[220:223], v157 offset:35840
	ds_read_b128 v[236:239], v157 offset:36864
	ds_read_b128 v[240:243], v157 offset:37888
	ds_read_b128 v[244:247], v157 offset:38912
	ds_read_b128 v[248:251], v157 offset:39936
	global_load_lds_dwordx4 v[252:253], off
	v_lshl_add_u64 v[252:253], s[36:37], 0, v[132:133]
	s_mov_b32 m0, s51
	s_nop 0
	global_load_lds_dwordx4 v[252:253], off
	s_waitcnt vmcnt(8)
	s_waitcnt lgkmcnt(0)
	s_barrier
	s_waitcnt lgkmcnt(0)
	v_mfma_f32_16x16x32_bf16 v[126:129], v[142:145], v[196:199], v[126:129]
	v_mfma_f32_16x16x32_bf16 v[118:121], v[172:175], v[196:199], v[118:121]
	v_mfma_f32_16x16x32_bf16 v[110:113], v[142:145], v[204:207], v[110:113]
	v_mfma_f32_16x16x32_bf16 v[102:105], v[172:175], v[204:207], v[102:105]
	v_mfma_f32_16x16x32_bf16 v[94:97], v[142:145], v[236:239], v[94:97]
	v_mfma_f32_16x16x32_bf16 v[86:89], v[172:175], v[236:239], v[86:89]
	v_mfma_f32_16x16x32_bf16 v[78:81], v[142:145], v[244:247], v[78:81]
	v_mfma_f32_16x16x32_bf16 v[70:73], v[172:175], v[244:247], v[70:73]
	v_mfma_f32_16x16x32_bf16 v[126:129], v[168:171], v[200:203], v[126:129]
	v_mfma_f32_16x16x32_bf16 v[118:121], v[176:179], v[200:203], v[118:121]
	v_mfma_f32_16x16x32_bf16 v[110:113], v[168:171], v[220:223], v[110:113]
	v_mfma_f32_16x16x32_bf16 v[102:105], v[176:179], v[220:223], v[102:105]
	v_mfma_f32_16x16x32_bf16 v[94:97], v[168:171], v[240:243], v[94:97]
	v_mfma_f32_16x16x32_bf16 v[86:89], v[176:179], v[240:243], v[86:89]
	v_mfma_f32_16x16x32_bf16 v[78:81], v[168:171], v[248:251], v[78:81]
	v_mfma_f32_16x16x32_bf16 v[70:73], v[176:179], v[248:251], v[70:73]
	v_mfma_f32_16x16x32_bf16 v[122:125], v[180:183], v[196:199], v[122:125]
	v_mfma_f32_16x16x32_bf16 v[114:117], v[188:191], v[196:199], v[114:117]
	v_mfma_f32_16x16x32_bf16 v[106:109], v[180:183], v[204:207], v[106:109]
	v_mfma_f32_16x16x32_bf16 v[98:101], v[188:191], v[204:207], v[98:101]
	v_mfma_f32_16x16x32_bf16 v[90:93], v[180:183], v[236:239], v[90:93]
	v_mfma_f32_16x16x32_bf16 v[82:85], v[188:191], v[236:239], v[82:85]
	v_mfma_f32_16x16x32_bf16 v[74:77], v[180:183], v[244:247], v[74:77]
	v_mfma_f32_16x16x32_bf16 v[66:69], v[188:191], v[244:247], v[66:69]
	v_mfma_f32_16x16x32_bf16 v[122:125], v[184:187], v[200:203], v[122:125]
	v_mfma_f32_16x16x32_bf16 v[114:117], v[192:195], v[200:203], v[114:117]
	v_mfma_f32_16x16x32_bf16 v[106:109], v[184:187], v[220:223], v[106:109]
	v_mfma_f32_16x16x32_bf16 v[98:101], v[192:195], v[220:223], v[98:101]
	v_mfma_f32_16x16x32_bf16 v[90:93], v[184:187], v[240:243], v[90:93]
	v_mfma_f32_16x16x32_bf16 v[82:85], v[192:195], v[240:243], v[82:85]
	v_mfma_f32_16x16x32_bf16 v[74:77], v[184:187], v[248:251], v[74:77]
	v_mfma_f32_16x16x32_bf16 v[66:69], v[192:195], v[248:251], v[66:69]
	s_barrier
	s_add_i32 s36, s57, s44
	v_lshl_add_u64 v[146:147], v[146:147], 0, s[96:97]
	s_mov_b32 m0, s36
	ds_read_b128 v[196:199], v157 offset:49152
	ds_read_b128 v[200:203], v157 offset:50176
	ds_read_b128 v[204:207], v157 offset:51200
	ds_read_b128 v[220:223], v157 offset:52224
	ds_read_b128 v[236:239], v157 offset:53248
	ds_read_b128 v[240:243], v157 offset:54272
	ds_read_b128 v[244:247], v157 offset:55296
	ds_read_b128 v[248:251], v157 offset:56320
	global_load_lds_dwordx4 v[146:147], off
	s_add_i32 m0, s36, 0x2000
	s_add_u32 s34, s34, 0x40080
	v_lshl_add_u64 v[146:147], v[208:209], 0, s[96:97]
	s_addc_u32 s35, s35, 0
	s_add_i32 s36, s58, s44
	global_load_lds_dwordx4 v[146:147], off
	v_lshl_add_u64 v[146:147], s[34:35], 0, v[134:135]
	s_mov_b32 m0, s36
	s_nop 0
	global_load_lds_dwordx4 v[146:147], off
	v_lshl_add_u64 v[146:147], s[34:35], 0, v[130:131]
	s_add_i32 m0, s36, 0x2000
	s_nop 0
	global_load_lds_dwordx4 v[146:147], off
	v_lshl_add_u64 v[146:147], v[224:225], 0, s[96:97]
	s_mov_b32 m0, s52
	s_nop 0
	global_load_lds_dwordx4 v[146:147], off
	v_lshl_add_u64 v[146:147], v[230:231], 0, s[96:97]
	s_mov_b32 m0, s53
	s_nop 0
	global_load_lds_dwordx4 v[146:147], off
	s_waitcnt vmcnt(8)
	s_waitcnt lgkmcnt(0)
	s_barrier
	s_waitcnt lgkmcnt(0)
	v_mfma_f32_16x16x32_bf16 v[62:65], v[142:145], v[196:199], v[62:65]
	v_mfma_f32_16x16x32_bf16 v[54:57], v[172:175], v[196:199], v[54:57]
	v_mfma_f32_16x16x32_bf16 v[46:49], v[142:145], v[204:207], v[46:49]
	v_mfma_f32_16x16x32_bf16 v[38:41], v[172:175], v[204:207], v[38:41]
	v_mfma_f32_16x16x32_bf16 v[30:33], v[142:145], v[236:239], v[30:33]
	v_mfma_f32_16x16x32_bf16 v[22:25], v[172:175], v[236:239], v[22:25]
	v_mfma_f32_16x16x32_bf16 v[14:17], v[142:145], v[244:247], v[14:17]
	v_mfma_f32_16x16x32_bf16 v[6:9], v[172:175], v[244:247], v[6:9]
	v_mfma_f32_16x16x32_bf16 v[62:65], v[168:171], v[200:203], v[62:65]
	v_mfma_f32_16x16x32_bf16 v[54:57], v[176:179], v[200:203], v[54:57]
	v_mfma_f32_16x16x32_bf16 v[46:49], v[168:171], v[220:223], v[46:49]
	v_mfma_f32_16x16x32_bf16 v[38:41], v[176:179], v[220:223], v[38:41]
	v_mfma_f32_16x16x32_bf16 v[30:33], v[168:171], v[240:243], v[30:33]
	v_mfma_f32_16x16x32_bf16 v[22:25], v[176:179], v[240:243], v[22:25]
	v_mfma_f32_16x16x32_bf16 v[14:17], v[168:171], v[248:251], v[14:17]
	v_mfma_f32_16x16x32_bf16 v[6:9], v[176:179], v[248:251], v[6:9]
	v_mfma_f32_16x16x32_bf16 v[58:61], v[180:183], v[196:199], v[58:61]
	v_mfma_f32_16x16x32_bf16 v[50:53], v[188:191], v[196:199], v[50:53]
	v_mfma_f32_16x16x32_bf16 v[42:45], v[180:183], v[204:207], v[42:45]
	v_mfma_f32_16x16x32_bf16 v[34:37], v[188:191], v[204:207], v[34:37]
	v_mfma_f32_16x16x32_bf16 v[26:29], v[180:183], v[236:239], v[26:29]
	v_mfma_f32_16x16x32_bf16 v[18:21], v[188:191], v[236:239], v[18:21]
	v_mfma_f32_16x16x32_bf16 v[10:13], v[180:183], v[244:247], v[10:13]
	v_mfma_f32_16x16x32_bf16 v[2:5], v[188:191], v[244:247], v[2:5]
	v_mfma_f32_16x16x32_bf16 v[58:61], v[184:187], v[200:203], v[58:61]
	v_mfma_f32_16x16x32_bf16 v[50:53], v[192:195], v[200:203], v[50:53]
	v_mfma_f32_16x16x32_bf16 v[42:45], v[184:187], v[220:223], v[42:45]
	v_mfma_f32_16x16x32_bf16 v[34:37], v[192:195], v[220:223], v[34:37]
	v_mfma_f32_16x16x32_bf16 v[26:29], v[184:187], v[240:243], v[26:29]
	v_mfma_f32_16x16x32_bf16 v[18:21], v[192:195], v[240:243], v[18:21]
	v_mfma_f32_16x16x32_bf16 v[10:13], v[184:187], v[248:251], v[10:13]
	v_mfma_f32_16x16x32_bf16 v[2:5], v[192:195], v[248:251], v[2:5]
	s_barrier
	s_add_i32 s56, s56, 2
	s_add_u32 s41, s41, 0x100
	s_addc_u32 s43, s43, 0
	s_add_u32 s30, s30, 0x100
	s_addc_u32 s31, s31, 0
	s_cmp_gt_u32 s56, 13
	s_cbranch_scc0 .LBB0_363
	s_and_b64 vcc, exec, s[16:17]
	s_cbranch_vccz .LBB0_366
	s_barrier

.LBB0_461:
	v_bfe_i32 v3, v234, 27, 1
	v_lshlrev_b32_e32 v1, 4, v234
	v_lshrrev_b32_e32 v3, 22, v3
	v_add_u32_e32 v3, v1, v3
	v_and_b32_e32 v3, 0xfffffc00, v3
	v_sub_u32_e32 v3, v1, v3
	s_ashr_i32 s8, s6, 3
	v_ashrrev_i32_e32 v2, 31, v234
	v_lshrrev_b32_e32 v4, 4, v3
	s_cmp_lg_u32 s74, 14
	v_lshrrev_b32_e32 v2, 26, v2
	v_bitop3_b32 v3, v4, v3, 32 bitop3:0x6c
	s_cselect_b64 s[14:15], -1, 0
	s_cmp_eq_u32 s74, 14
	v_add_u32_e32 v2, v234, v2
	v_ashrrev_i32_e32 v5, 31, v3
	s_cselect_b64 s[4:5], -1, 0
	v_ashrrev_i32_e32 v2, 6, v2
	v_lshrrev_b32_e32 v5, 26, v5
	s_or_b64 s[4:5], s[20:21], s[4:5]
	v_lshlrev_b32_e32 v4, 3, v2
	v_add_u32_e32 v5, v3, v5
	s_and_b64 s[4:5], s[4:5], exec
	v_and_b32_e32 v4, -16, v4
	v_ashrrev_i32_e32 v6, 6, v5
	s_movk_i32 s4, 0xb00
	v_add_u32_e32 v4, v6, v4
	v_and_b32_e32 v5, 0xc0, v5
	s_cselect_b32 s6, s4, 0x400
	v_sub_u32_e32 v3, v3, v5
	v_lshlrev_b32_e32 v7, 1, v4
	v_lshrrev_b32_e32 v8, 2, v4
	v_and_b32_e32 v6, 3, v6
	s_mov_b32 s4, 0xffffe0
	v_lshlrev_b32_e32 v2, 5, v2
	v_ashrrev_i16_sdwa v3, v226, sext(v3) dst_sel:DWORD dst_unused:UNUSED_PAD src0_sel:DWORD src1_sel:BYTE_0
	v_and_b32_e32 v7, 24, v7
	v_and_b32_e32 v8, 4, v8
	v_and_or_b32 v6, v4, s4, v6
	v_and_b32_e32 v2, 32, v2
	v_bfe_i32 v3, v3, 0, 16
	v_or3_b32 v6, v6, v8, v7
	v_add_u32_e32 v5, v2, v3
	v_mul_lo_u32 v4, v4, s6
	v_mul_u32_u24_e32 v6, s6, v6
	v_add_u32_e32 v1, 0x2000, v1
	s_waitcnt vmcnt(0)
	v_add_lshl_u32 v130, v5, v4, 1
	v_add_lshl_u32 v132, v6, v5, 1
	v_ashrrev_i32_e32 v5, 31, v1
	v_lshrrev_b32_e32 v5, 22, v5
	v_add_u32_e32 v5, v1, v5
	v_ashrrev_i32_e32 v5, 10, v5
	v_mul_i32_i24_e32 v6, 0x400, v5
	v_sub_u32_e32 v1, v1, v6
	v_lshrrev_b32_e32 v6, 4, v1
	v_bitop3_b32 v1, v6, v1, 32 bitop3:0x6c
	v_ashrrev_i32_e32 v7, 31, v1
	v_lshrrev_b32_e32 v7, 26, v7
	v_lshlrev_b32_e32 v6, 3, v5
	v_add_u32_e32 v7, v1, v7
	s_ashr_i32 s13, s43, 6
	v_and_b32_e32 v6, -16, v6
	v_ashrrev_i32_e32 v8, 6, v7
	s_ashr_i32 s40, s43, 8
	v_add_u32_e32 v9, v8, v6
	v_and_b32_e32 v8, 3, v8
	s_lshl_b32 s45, s6, 8
	s_lshl_b32 s46, s6, 9
	s_lshl_b32 s47, s13, 10
	v_and_or_b32 v8, v9, s4, v8
	s_and_b64 s[4:5], s[20:21], exec
	s_mov_b32 s4, 0x5c80000
	s_cselect_b32 s9, s4, 0x2400000
	s_and_b64 s[4:5], s[16:17], exec
	s_cselect_b32 s9, 0x1700000, s9
	s_and_b64 s[4:5], exec, s[18:19]
	s_cselect_b32 s4, 0x4f80000, s9
	s_add_u32 s48, s0, s4
	s_addc_u32 s49, s1, 0
	s_add_i32 s4, s7, s8
	s_ashr_i32 s5, s4, 31
	s_lshr_b32 s5, s5, 27
	s_add_i32 s5, s4, s5
	s_ashr_i32 s7, s5, 5
	s_and_b32 s5, s5, 0xffe0
	s_sub_i32 s4, s4, s5
	s_bfe_i32 s5, s4, 0x80000
	s_bfe_u32 s5, s5, 0x3000c
	s_add_i32 s5, s4, s5
	s_lshl_b32 s8, s7, 3
	s_bfe_i32 s7, s5, 0x80000
	s_and_b32 s5, s5, 0xf8
	s_sub_i32 s4, s4, s5
	s_sext_i32_i16 s7, s7
	s_sext_i32_i8 s4, s4
	s_add_i32 s50, s8, s4
	s_ashr_i32 s4, s7, 3
	v_and_b32_e32 v6, 0xc0, v7
	s_mul_hi_i32 s5, s46, s4
	s_mul_i32 s4, s46, s4
	v_sub_u32_e32 v1, v1, v6
	v_lshlrev_b32_e32 v7, 1, v9
	v_lshrrev_b32_e32 v10, 2, v9
	s_add_u32 s26, s48, s4
	v_lshlrev_b32_e32 v5, 5, v5
	v_ashrrev_i16_sdwa v1, v226, sext(v1) dst_sel:DWORD dst_unused:UNUSED_PAD src0_sel:DWORD src1_sel:BYTE_0
	v_and_b32_e32 v7, 24, v7
	v_and_b32_e32 v10, 4, v10
	s_addc_u32 s27, s49, s5
	s_add_i32 s51, s47, 0
	v_and_b32_e32 v5, 32, v5
	v_bfe_i32 v6, v1, 0, 16
	v_or3_b32 v8, v8, v10, v7
	s_add_i32 m0, s51, 0x10000
	v_add_u32_e32 v1, v5, v6
	v_mul_u32_u24_e32 v8, s6, v8
	global_load_lds_dwordx4 v132, s[26:27]
	s_add_i32 m0, s51, 0x12000
	v_add_lshl_u32 v136, v8, v1, 1
	s_add_u32 s4, s26, s45
	global_load_lds_dwordx4 v136, s[26:27]
	s_addc_u32 s5, s27, 0
	s_add_i32 m0, s51, 0x14000
	s_mul_i32 s9, s46, s50
	global_load_lds_dwordx4 v132, s[4:5]
	s_add_i32 m0, s51, 0x16000
	s_mul_hi_i32 s8, s46, s50
	s_add_u32 s28, s22, s9
	s_addc_u32 s29, s23, s8
	s_add_i32 s52, s51, 0x2000
	v_mul_lo_u32 v7, v9, s6
	global_load_lds_dwordx4 v136, s[4:5]
	s_mov_b32 m0, s51
	s_add_u32 s8, s28, s45
	v_add_lshl_u32 v134, v1, v7, 1
	global_load_lds_dwordx4 v130, s[28:29]
	s_mov_b32 m0, s52
	s_addc_u32 s9, s29, 0
	s_add_i32 s53, s51, 0x4000
	global_load_lds_dwordx4 v134, s[28:29]
	s_mov_b32 m0, s53
	s_add_i32 s54, s51, 0x6000
	global_load_lds_dwordx4 v130, s[8:9]
	s_mov_b32 m0, s54
	s_cmp_lg_u32 s40, 1
	global_load_lds_dwordx4 v134, s[8:9]
	s_cbranch_scc1 .LBB0_463
	s_setprio 1
	s_barrier

.LBB0_476:
	s_add_i32 s63, s31, 2
	s_add_u32 s38, s28, s36
	s_addc_u32 s39, s29, s37
	s_add_u32 s64, s26, s36
	s_addc_u32 s65, s27, s37
	s_add_i32 s66, 0, 0x10000
	s_cmp_eq_u32 s59, s31
	s_cselect_b32 s39, s9, s39
	s_cselect_b32 s38, s8, s38
	s_cselect_b32 s65, s35, s65
	s_cselect_b32 s64, s34, s64
	s_add_i32 s31, 0, 0x14000
	v_add_u32_e32 v160, s66, v146
	v_add_u32_e32 v176, s31, v146
	ds_read_b128 v[148:151], v160
	ds_read_b128 v[152:155], v160 offset:1024
	ds_read_b128 v[156:159], v160 offset:2048
	ds_read_b128 v[160:163], v160 offset:3072
	ds_read_b128 v[164:167], v176
	ds_read_b128 v[168:171], v176 offset:1024
	ds_read_b128 v[172:175], v176 offset:2048
	ds_read_b128 v[176:179], v176 offset:3072
	v_lshl_add_u64 v[208:209], s[28:29], 0, v[142:143]
	s_add_i32 m0, s51, 0xc000
	ds_read_b128 v[180:183], v147
	ds_read_b128 v[184:187], v147 offset:1024
	ds_read_b128 v[188:191], v147 offset:2048
	ds_read_b128 v[192:195], v147 offset:3072
	ds_read_b128 v[196:199], v147 offset:4096
	ds_read_b128 v[200:203], v147 offset:5120
	ds_read_b128 v[204:207], v147 offset:6144
	ds_read_b128 v[220:223], v147 offset:7168
	global_load_lds_dwordx4 v[208:209], off
	v_lshl_add_u64 v[208:209], s[28:29], 0, v[144:145]
	s_add_i32 m0, s51, 0xe000
	s_nop 0
	global_load_lds_dwordx4 v[208:209], off
	s_waitcnt vmcnt(8)
	s_waitcnt lgkmcnt(0)
	s_barrier
	s_waitcnt lgkmcnt(0)
	v_mfma_f32_16x16x32_bf16 v[126:129], v[148:151], v[180:183], v[126:129]
	v_mfma_f32_16x16x32_bf16 v[122:125], v[156:159], v[180:183], v[122:125]
	v_mfma_f32_16x16x32_bf16 v[110:113], v[148:151], v[188:191], v[110:113]
	v_mfma_f32_16x16x32_bf16 v[106:109], v[156:159], v[188:191], v[106:109]
	v_mfma_f32_16x16x32_bf16 v[94:97], v[148:151], v[196:199], v[94:97]
	v_mfma_f32_16x16x32_bf16 v[90:93], v[156:159], v[196:199], v[90:93]
	v_mfma_f32_16x16x32_bf16 v[78:81], v[148:151], v[204:207], v[78:81]
	v_mfma_f32_16x16x32_bf16 v[74:77], v[156:159], v[204:207], v[74:77]
	v_mfma_f32_16x16x32_bf16 v[126:129], v[152:155], v[184:187], v[126:129]
	v_mfma_f32_16x16x32_bf16 v[122:125], v[160:163], v[184:187], v[122:125]
	v_mfma_f32_16x16x32_bf16 v[110:113], v[152:155], v[192:195], v[110:113]
	v_mfma_f32_16x16x32_bf16 v[106:109], v[160:163], v[192:195], v[106:109]
	v_mfma_f32_16x16x32_bf16 v[94:97], v[152:155], v[200:203], v[94:97]
	v_mfma_f32_16x16x32_bf16 v[90:93], v[160:163], v[200:203], v[90:93]
	v_mfma_f32_16x16x32_bf16 v[78:81], v[152:155], v[220:223], v[78:81]
	v_mfma_f32_16x16x32_bf16 v[74:77], v[160:163], v[220:223], v[74:77]
	v_mfma_f32_16x16x32_bf16 v[118:121], v[164:167], v[180:183], v[118:121]
	v_mfma_f32_16x16x32_bf16 v[114:117], v[172:175], v[180:183], v[114:117]
	v_mfma_f32_16x16x32_bf16 v[102:105], v[164:167], v[188:191], v[102:105]
	v_mfma_f32_16x16x32_bf16 v[98:101], v[172:175], v[188:191], v[98:101]
	v_mfma_f32_16x16x32_bf16 v[86:89], v[164:167], v[196:199], v[86:89]
	v_mfma_f32_16x16x32_bf16 v[82:85], v[172:175], v[196:199], v[82:85]
	v_mfma_f32_16x16x32_bf16 v[70:73], v[164:167], v[204:207], v[70:73]
	v_mfma_f32_16x16x32_bf16 v[66:69], v[172:175], v[204:207], v[66:69]
	v_mfma_f32_16x16x32_bf16 v[118:121], v[168:171], v[184:187], v[118:121]
	v_mfma_f32_16x16x32_bf16 v[114:117], v[176:179], v[184:187], v[114:117]
	v_mfma_f32_16x16x32_bf16 v[102:105], v[168:171], v[192:195], v[102:105]
	v_mfma_f32_16x16x32_bf16 v[98:101], v[176:179], v[192:195], v[98:101]
	v_mfma_f32_16x16x32_bf16 v[86:89], v[168:171], v[200:203], v[86:89]
	v_mfma_f32_16x16x32_bf16 v[82:85], v[176:179], v[200:203], v[82:85]
	v_mfma_f32_16x16x32_bf16 v[70:73], v[168:171], v[220:223], v[70:73]
	v_mfma_f32_16x16x32_bf16 v[66:69], v[176:179], v[220:223], v[66:69]
	s_barrier
	s_add_i32 s66, s66, s47
	v_lshl_add_u64 v[208:209], s[64:65], 0, v[132:133]
	s_mov_b32 m0, s66
	ds_read_b128 v[180:183], v147 offset:16384
	ds_read_b128 v[184:187], v147 offset:17408
	ds_read_b128 v[188:191], v147 offset:18432
	ds_read_b128 v[192:195], v147 offset:19456
	ds_read_b128 v[196:199], v147 offset:20480
	ds_read_b128 v[200:203], v147 offset:21504
	ds_read_b128 v[204:207], v147 offset:22528
	ds_read_b128 v[220:223], v147 offset:23552
	global_load_lds_dwordx4 v[208:209], off
	s_add_i32 m0, s66, 0x2000
	v_lshl_add_u64 v[224:225], s[64:65], 0, v[136:137]
	s_add_u32 s64, s64, s45
	s_addc_u32 s65, s65, 0
	s_add_i32 s31, s31, s47
	global_load_lds_dwordx4 v[224:225], off
	v_lshl_add_u64 v[230:231], s[64:65], 0, v[132:133]
	s_mov_b32 m0, s31
	v_lshl_add_u64 v[236:237], s[64:65], 0, v[136:137]
	global_load_lds_dwordx4 v[230:231], off
	s_add_i32 m0, s31, 0x2000
	v_lshl_add_u64 v[238:239], s[38:39], 0, v[130:131]
	global_load_lds_dwordx4 v[236:237], off
	s_mov_b32 m0, s51
	v_lshl_add_u64 v[240:241], s[38:39], 0, v[134:135]
	global_load_lds_dwordx4 v[238:239], off
	s_mov_b32 m0, s52
	s_nop 0
	global_load_lds_dwordx4 v[240:241], off
	s_waitcnt vmcnt(8)
	s_waitcnt lgkmcnt(0)
	s_barrier
	s_waitcnt lgkmcnt(0)
	v_mfma_f32_16x16x32_bf16 v[62:65], v[148:151], v[180:183], v[62:65]
	v_mfma_f32_16x16x32_bf16 v[58:61], v[156:159], v[180:183], v[58:61]
	v_mfma_f32_16x16x32_bf16 v[46:49], v[148:151], v[188:191], v[46:49]
	v_mfma_f32_16x16x32_bf16 v[42:45], v[156:159], v[188:191], v[42:45]
	v_mfma_f32_16x16x32_bf16 v[30:33], v[148:151], v[196:199], v[30:33]
	v_mfma_f32_16x16x32_bf16 v[26:29], v[156:159], v[196:199], v[26:29]
	v_mfma_f32_16x16x32_bf16 v[14:17], v[148:151], v[204:207], v[14:17]
	v_mfma_f32_16x16x32_bf16 v[10:13], v[156:159], v[204:207], v[10:13]
	v_mfma_f32_16x16x32_bf16 v[62:65], v[152:155], v[184:187], v[62:65]
	v_mfma_f32_16x16x32_bf16 v[58:61], v[160:163], v[184:187], v[58:61]
	v_mfma_f32_16x16x32_bf16 v[46:49], v[152:155], v[192:195], v[46:49]
	v_mfma_f32_16x16x32_bf16 v[42:45], v[160:163], v[192:195], v[42:45]
	v_mfma_f32_16x16x32_bf16 v[30:33], v[152:155], v[200:203], v[30:33]
	v_mfma_f32_16x16x32_bf16 v[26:29], v[160:163], v[200:203], v[26:29]
	v_mfma_f32_16x16x32_bf16 v[14:17], v[152:155], v[220:223], v[14:17]
	v_mfma_f32_16x16x32_bf16 v[10:13], v[160:163], v[220:223], v[10:13]
	v_mfma_f32_16x16x32_bf16 v[54:57], v[164:167], v[180:183], v[54:57]
	v_mfma_f32_16x16x32_bf16 v[50:53], v[172:175], v[180:183], v[50:53]
	v_mfma_f32_16x16x32_bf16 v[38:41], v[164:167], v[188:191], v[38:41]
	v_mfma_f32_16x16x32_bf16 v[34:37], v[172:175], v[188:191], v[34:37]
	v_mfma_f32_16x16x32_bf16 v[22:25], v[164:167], v[196:199], v[22:25]
	v_mfma_f32_16x16x32_bf16 v[18:21], v[172:175], v[196:199], v[18:21]
	v_mfma_f32_16x16x32_bf16 v[6:9], v[164:167], v[204:207], v[6:9]
	v_mfma_f32_16x16x32_bf16 v[2:5], v[172:175], v[204:207], v[2:5]
	v_mfma_f32_16x16x32_bf16 v[54:57], v[168:171], v[184:187], v[54:57]
	v_mfma_f32_16x16x32_bf16 v[50:53], v[176:179], v[184:187], v[50:53]
	v_mfma_f32_16x16x32_bf16 v[38:41], v[168:171], v[192:195], v[38:41]
	v_mfma_f32_16x16x32_bf16 v[34:37], v[176:179], v[192:195], v[34:37]
	v_mfma_f32_16x16x32_bf16 v[22:25], v[168:171], v[200:203], v[22:25]
	v_mfma_f32_16x16x32_bf16 v[18:21], v[176:179], v[200:203], v[18:21]
	v_mfma_f32_16x16x32_bf16 v[6:9], v[168:171], v[220:223], v[6:9]
	v_mfma_f32_16x16x32_bf16 v[2:5], v[176:179], v[220:223], v[2:5]
	s_barrier
	s_add_i32 s31, 0, 0x18000
	s_add_i32 s64, 0, 0x1c000
	v_add_u32_e32 v160, s31, v146
	v_add_u32_e32 v176, s64, v146
	ds_read_b128 v[148:151], v160
	ds_read_b128 v[152:155], v160 offset:1024
	ds_read_b128 v[156:159], v160 offset:2048
	ds_read_b128 v[160:163], v160 offset:3072
	ds_read_b128 v[164:167], v176
	ds_read_b128 v[168:171], v176 offset:1024
	ds_read_b128 v[172:175], v176 offset:2048
	ds_read_b128 v[176:179], v176 offset:3072
	s_add_u32 s38, s38, s45
	s_addc_u32 s39, s39, 0
	s_mov_b32 m0, s53
	v_lshl_add_u64 v[242:243], s[38:39], 0, v[130:131]
	ds_read_b128 v[180:183], v147 offset:32768
	ds_read_b128 v[184:187], v147 offset:33792
	ds_read_b128 v[188:191], v147 offset:34816
	ds_read_b128 v[192:195], v147 offset:35840
	ds_read_b128 v[196:199], v147 offset:36864
	ds_read_b128 v[200:203], v147 offset:37888
	ds_read_b128 v[204:207], v147 offset:38912
	ds_read_b128 v[220:223], v147 offset:39936
	global_load_lds_dwordx4 v[242:243], off
	v_lshl_add_u64 v[242:243], s[38:39], 0, v[134:135]
	s_mov_b32 m0, s54
	s_nop 0
	global_load_lds_dwordx4 v[242:243], off
	s_waitcnt vmcnt(8)
	s_waitcnt lgkmcnt(0)
	s_barrier
	s_waitcnt lgkmcnt(0)
	v_mfma_f32_16x16x32_bf16 v[126:129], v[148:151], v[180:183], v[126:129]
	v_mfma_f32_16x16x32_bf16 v[122:125], v[156:159], v[180:183], v[122:125]
	v_mfma_f32_16x16x32_bf16 v[110:113], v[148:151], v[188:191], v[110:113]
	v_mfma_f32_16x16x32_bf16 v[106:109], v[156:159], v[188:191], v[106:109]
	v_mfma_f32_16x16x32_bf16 v[94:97], v[148:151], v[196:199], v[94:97]
	v_mfma_f32_16x16x32_bf16 v[90:93], v[156:159], v[196:199], v[90:93]
	v_mfma_f32_16x16x32_bf16 v[78:81], v[148:151], v[204:207], v[78:81]
	v_mfma_f32_16x16x32_bf16 v[74:77], v[156:159], v[204:207], v[74:77]
	v_mfma_f32_16x16x32_bf16 v[126:129], v[152:155], v[184:187], v[126:129]
	v_mfma_f32_16x16x32_bf16 v[122:125], v[160:163], v[184:187], v[122:125]
	v_mfma_f32_16x16x32_bf16 v[110:113], v[152:155], v[192:195], v[110:113]
	v_mfma_f32_16x16x32_bf16 v[106:109], v[160:163], v[192:195], v[106:109]
	v_mfma_f32_16x16x32_bf16 v[94:97], v[152:155], v[200:203], v[94:97]
	v_mfma_f32_16x16x32_bf16 v[90:93], v[160:163], v[200:203], v[90:93]
	v_mfma_f32_16x16x32_bf16 v[78:81], v[152:155], v[220:223], v[78:81]
	v_mfma_f32_16x16x32_bf16 v[74:77], v[160:163], v[220:223], v[74:77]
	v_mfma_f32_16x16x32_bf16 v[118:121], v[164:167], v[180:183], v[118:121]
	v_mfma_f32_16x16x32_bf16 v[114:117], v[172:175], v[180:183], v[114:117]
	v_mfma_f32_16x16x32_bf16 v[102:105], v[164:167], v[188:191], v[102:105]
	v_mfma_f32_16x16x32_bf16 v[98:101], v[172:175], v[188:191], v[98:101]
	v_mfma_f32_16x16x32_bf16 v[86:89], v[164:167], v[196:199], v[86:89]
	v_mfma_f32_16x16x32_bf16 v[82:85], v[172:175], v[196:199], v[82:85]
	v_mfma_f32_16x16x32_bf16 v[70:73], v[164:167], v[204:207], v[70:73]
	v_mfma_f32_16x16x32_bf16 v[66:69], v[172:175], v[204:207], v[66:69]
	v_mfma_f32_16x16x32_bf16 v[118:121], v[168:171], v[184:187], v[118:121]
	v_mfma_f32_16x16x32_bf16 v[114:117], v[176:179], v[184:187], v[114:117]
	v_mfma_f32_16x16x32_bf16 v[102:105], v[168:171], v[192:195], v[102:105]
	v_mfma_f32_16x16x32_bf16 v[98:101], v[176:179], v[192:195], v[98:101]
	v_mfma_f32_16x16x32_bf16 v[86:89], v[168:171], v[200:203], v[86:89]
	v_mfma_f32_16x16x32_bf16 v[82:85], v[176:179], v[200:203], v[82:85]
	v_mfma_f32_16x16x32_bf16 v[70:73], v[168:171], v[220:223], v[70:73]
	v_mfma_f32_16x16x32_bf16 v[66:69], v[176:179], v[220:223], v[66:69]
	s_barrier
	s_add_i32 s31, s31, s47
	v_lshl_add_u64 v[208:209], v[208:209], 0, s[96:97]
	s_mov_b32 m0, s31
	ds_read_b128 v[180:183], v147 offset:49152
	ds_read_b128 v[184:187], v147 offset:50176
	ds_read_b128 v[188:191], v147 offset:51200
	ds_read_b128 v[192:195], v147 offset:52224
	ds_read_b128 v[196:199], v147 offset:53248
	ds_read_b128 v[200:203], v147 offset:54272
	ds_read_b128 v[204:207], v147 offset:55296
	ds_read_b128 v[220:223], v147 offset:56320
	global_load_lds_dwordx4 v[208:209], off
	v_lshl_add_u64 v[208:209], v[224:225], 0, s[96:97]
	s_add_i32 m0, s31, 0x2000
	s_add_i32 s31, s64, s47
	global_load_lds_dwordx4 v[208:209], off
	v_lshl_add_u64 v[208:209], v[230:231], 0, s[96:97]
	s_mov_b32 m0, s31
	s_nop 0
	global_load_lds_dwordx4 v[208:209], off
	v_lshl_add_u64 v[208:209], v[236:237], 0, s[96:97]
	s_add_i32 m0, s31, 0x2000
	s_nop 0
	global_load_lds_dwordx4 v[208:209], off
	v_lshl_add_u64 v[208:209], v[238:239], 0, s[96:97]
	s_mov_b32 m0, s57
	s_nop 0
	global_load_lds_dwordx4 v[208:209], off
	v_lshl_add_u64 v[208:209], v[240:241], 0, s[96:97]
	s_mov_b32 m0, s58
	s_nop 0
	global_load_lds_dwordx4 v[208:209], off
	s_waitcnt vmcnt(8)
	s_waitcnt lgkmcnt(0)
	s_barrier
	s_waitcnt lgkmcnt(0)
	v_mfma_f32_16x16x32_bf16 v[62:65], v[148:151], v[180:183], v[62:65]
	v_mfma_f32_16x16x32_bf16 v[58:61], v[156:159], v[180:183], v[58:61]
	v_mfma_f32_16x16x32_bf16 v[46:49], v[148:151], v[188:191], v[46:49]
	v_mfma_f32_16x16x32_bf16 v[42:45], v[156:159], v[188:191], v[42:45]
	v_mfma_f32_16x16x32_bf16 v[30:33], v[148:151], v[196:199], v[30:33]
	v_mfma_f32_16x16x32_bf16 v[26:29], v[156:159], v[196:199], v[26:29]
	v_mfma_f32_16x16x32_bf16 v[14:17], v[148:151], v[204:207], v[14:17]
	v_mfma_f32_16x16x32_bf16 v[10:13], v[156:159], v[204:207], v[10:13]
	v_mfma_f32_16x16x32_bf16 v[62:65], v[152:155], v[184:187], v[62:65]
	v_mfma_f32_16x16x32_bf16 v[58:61], v[160:163], v[184:187], v[58:61]
	v_mfma_f32_16x16x32_bf16 v[46:49], v[152:155], v[192:195], v[46:49]
	v_mfma_f32_16x16x32_bf16 v[42:45], v[160:163], v[192:195], v[42:45]
	v_mfma_f32_16x16x32_bf16 v[30:33], v[152:155], v[200:203], v[30:33]
	v_mfma_f32_16x16x32_bf16 v[26:29], v[160:163], v[200:203], v[26:29]
	v_mfma_f32_16x16x32_bf16 v[14:17], v[152:155], v[220:223], v[14:17]
	v_mfma_f32_16x16x32_bf16 v[10:13], v[160:163], v[220:223], v[10:13]
	v_mfma_f32_16x16x32_bf16 v[54:57], v[164:167], v[180:183], v[54:57]
	v_mfma_f32_16x16x32_bf16 v[50:53], v[172:175], v[180:183], v[50:53]
	v_mfma_f32_16x16x32_bf16 v[38:41], v[164:167], v[188:191], v[38:41]
	v_mfma_f32_16x16x32_bf16 v[34:37], v[172:175], v[188:191], v[34:37]
	v_mfma_f32_16x16x32_bf16 v[22:25], v[164:167], v[196:199], v[22:25]
	v_mfma_f32_16x16x32_bf16 v[18:21], v[172:175], v[196:199], v[18:21]
	v_mfma_f32_16x16x32_bf16 v[6:9], v[164:167], v[204:207], v[6:9]
	v_mfma_f32_16x16x32_bf16 v[2:5], v[172:175], v[204:207], v[2:5]
	v_mfma_f32_16x16x32_bf16 v[54:57], v[168:171], v[184:187], v[54:57]
	v_mfma_f32_16x16x32_bf16 v[50:53], v[176:179], v[184:187], v[50:53]
	v_mfma_f32_16x16x32_bf16 v[38:41], v[168:171], v[192:195], v[38:41]
	v_mfma_f32_16x16x32_bf16 v[34:37], v[176:179], v[192:195], v[34:37]
	v_mfma_f32_16x16x32_bf16 v[22:25], v[168:171], v[200:203], v[22:25]
	v_mfma_f32_16x16x32_bf16 v[18:21], v[176:179], v[200:203], v[18:21]
	v_mfma_f32_16x16x32_bf16 v[6:9], v[168:171], v[220:223], v[6:9]
	v_mfma_f32_16x16x32_bf16 v[2:5], v[176:179], v[220:223], v[2:5]
	s_barrier
	s_add_u32 s36, s36, 0x100
	s_addc_u32 s37, s37, 0
	v_lshl_add_u64 v[144:145], v[144:145], 0, s[2:3]
	v_lshl_add_u64 v[142:143], v[142:143], 0, s[2:3]
	s_cmp_ge_u32 s63, s56
	s_mov_b32 s31, s63
	s_cbranch_scc0 .LBB0_476
	s_and_b64 vcc, exec, s[6:7]
	s_cbranch_vccnz .LBB0_464
	v_mov_b32_e32 v2, 0
	s_mov_b32 s55, s61
	s_mov_b32 s50, s62
	s_mov_b64 s[26:27], s[34:35]
	s_mov_b64 s[28:29], s[8:9]
	s_mov_b32 s60, s30
	v_mov_b32_e32 v3, v2
	v_mov_b32_e32 v4, v2
	v_mov_b32_e32 v5, v2
	v_mov_b32_e32 v6, v2
	v_mov_b32_e32 v7, v2
	v_mov_b32_e32 v8, v2
	v_mov_b32_e32 v9, v2
	v_mov_b32_e32 v18, v2
	v_mov_b32_e32 v19, v2
	v_mov_b32_e32 v20, v2
	v_mov_b32_e32 v21, v2
	v_mov_b32_e32 v22, v2
	v_mov_b32_e32 v23, v2
	v_mov_b32_e32 v24, v2
	v_mov_b32_e32 v25, v2
	v_mov_b32_e32 v34, v2
	v_mov_b32_e32 v35, v2
	v_mov_b32_e32 v36, v2
	v_mov_b32_e32 v37, v2
	v_mov_b32_e32 v38, v2
	v_mov_b32_e32 v39, v2
	v_mov_b32_e32 v40, v2
	v_mov_b32_e32 v41, v2
	v_mov_b32_e32 v50, v2
	v_mov_b32_e32 v51, v2
	v_mov_b32_e32 v52, v2
	v_mov_b32_e32 v53, v2
	v_mov_b32_e32 v54, v2
	v_mov_b32_e32 v55, v2
	v_mov_b32_e32 v56, v2
	v_mov_b32_e32 v57, v2
	v_mov_b32_e32 v10, v2
	v_mov_b32_e32 v11, v2
	v_mov_b32_e32 v12, v2
	v_mov_b32_e32 v13, v2
	v_mov_b32_e32 v14, v2
	v_mov_b32_e32 v15, v2
	v_mov_b32_e32 v16, v2
	v_mov_b32_e32 v17, v2
	v_mov_b32_e32 v26, v2
	v_mov_b32_e32 v27, v2
	v_mov_b32_e32 v28, v2
	v_mov_b32_e32 v29, v2
	v_mov_b32_e32 v30, v2
	v_mov_b32_e32 v31, v2
	v_mov_b32_e32 v32, v2
	v_mov_b32_e32 v33, v2
	v_mov_b32_e32 v42, v2
	v_mov_b32_e32 v43, v2
	v_mov_b32_e32 v44, v2
	v_mov_b32_e32 v45, v2
	v_mov_b32_e32 v46, v2
	v_mov_b32_e32 v47, v2
	v_mov_b32_e32 v48, v2
	v_mov_b32_e32 v49, v2
	v_mov_b32_e32 v58, v2
	v_mov_b32_e32 v59, v2
	v_mov_b32_e32 v60, v2
	v_mov_b32_e32 v61, v2
	v_mov_b32_e32 v62, v2
	v_mov_b32_e32 v63, v2
	v_mov_b32_e32 v64, v2
	v_mov_b32_e32 v65, v2
	v_mov_b32_e32 v66, v2
	v_mov_b32_e32 v67, v2
	v_mov_b32_e32 v68, v2
	v_mov_b32_e32 v69, v2
	v_mov_b32_e32 v70, v2
	v_mov_b32_e32 v71, v2
	v_mov_b32_e32 v72, v2
	v_mov_b32_e32 v73, v2
	v_mov_b32_e32 v82, v2
	v_mov_b32_e32 v83, v2
	v_mov_b32_e32 v84, v2
	v_mov_b32_e32 v85, v2
	v_mov_b32_e32 v86, v2
	v_mov_b32_e32 v87, v2
	v_mov_b32_e32 v88, v2
	v_mov_b32_e32 v89, v2
	v_mov_b32_e32 v98, v2
	v_mov_b32_e32 v99, v2
	v_mov_b32_e32 v100, v2
	v_mov_b32_e32 v101, v2
	v_mov_b32_e32 v102, v2
	v_mov_b32_e32 v103, v2
	v_mov_b32_e32 v104, v2
	v_mov_b32_e32 v105, v2
	v_mov_b32_e32 v114, v2
	v_mov_b32_e32 v115, v2
	v_mov_b32_e32 v116, v2
	v_mov_b32_e32 v117, v2
	v_mov_b32_e32 v118, v2
	v_mov_b32_e32 v119, v2
	v_mov_b32_e32 v120, v2
	v_mov_b32_e32 v121, v2
	v_mov_b32_e32 v74, v2
	v_mov_b32_e32 v75, v2
	v_mov_b32_e32 v76, v2
	v_mov_b32_e32 v77, v2
	v_mov_b32_e32 v78, v2
	v_mov_b32_e32 v79, v2
	v_mov_b32_e32 v80, v2
	v_mov_b32_e32 v81, v2
	v_mov_b32_e32 v90, v2
	v_mov_b32_e32 v91, v2
	v_mov_b32_e32 v92, v2
	v_mov_b32_e32 v93, v2
	v_mov_b32_e32 v94, v2
	v_mov_b32_e32 v95, v2
	v_mov_b32_e32 v96, v2
	v_mov_b32_e32 v97, v2
	v_mov_b32_e32 v106, v2
	v_mov_b32_e32 v107, v2
	v_mov_b32_e32 v108, v2
	v_mov_b32_e32 v109, v2
	v_mov_b32_e32 v110, v2
	v_mov_b32_e32 v111, v2
	v_mov_b32_e32 v112, v2
	v_mov_b32_e32 v113, v2
	v_mov_b32_e32 v122, v2
	v_mov_b32_e32 v123, v2
	v_mov_b32_e32 v124, v2
	v_mov_b32_e32 v125, v2
	v_mov_b32_e32 v126, v2
	v_mov_b32_e32 v127, v2
	v_mov_b32_e32 v128, v2
	v_mov_b32_e32 v129, v2
	s_branch .LBB0_464

.LBB0_631:
	s_cmpk_gt_i32 s52, 0x2ff
	v_readfirstlane_b32 s5, v234
	s_cbranch_scc1 .LBB0_651
	v_lshlrev_b32_e32 v2, 4, v234
	s_waitcnt lgkmcnt(0)
	v_add_u32_e32 v3, 0x2000, v2
	v_ashrrev_i32_e32 v4, 31, v3
	v_lshrrev_b32_e32 v4, 22, v4
	v_add_u32_e32 v4, v3, v4
	v_ashrrev_i32_e32 v10, 10, v4
	v_mul_i32_i24_e32 v4, 0x400, v10
	v_sub_u32_e32 v3, v3, v4
	v_lshrrev_b32_e32 v4, 4, v3
	v_bitop3_b32 v3, v4, v3, 32 bitop3:0x6c
	v_ashrrev_i32_e32 v4, 31, v3
	v_lshrrev_b32_e32 v4, 26, v4
	v_add_u32_e32 v4, v3, v4
	v_lshlrev_b32_e32 v5, 3, v10
	v_ashrrev_i32_e32 v12, 6, v4
	v_and_b32_e32 v5, -16, v5
	v_add_u32_e32 v5, v12, v5
	v_and_b32_e32 v6, 3, v12
	s_mov_b32 s4, 0x1fffe0
	v_lshrrev_b32_e32 v7, 2, v5
	v_lshlrev_b32_e32 v8, 1, v5
	v_and_b32_e32 v4, 0xc0, v4
	v_and_or_b32 v6, v5, s4, v6
	v_and_b32_e32 v7, 4, v7
	v_and_b32_e32 v8, 24, v8
	v_sub_u32_e32 v3, v3, v4
	v_or3_b32 v6, v6, v7, v8
	v_lshlrev_b32_e32 v7, 5, v10
	v_ashrrev_i16_sdwa v3, v226, sext(v3) dst_sel:DWORD dst_unused:UNUSED_PAD src0_sel:DWORD src1_sel:BYTE_0
	v_and_b32_e32 v7, 32, v7
	v_bfe_i32 v13, v3, 0, 16
	v_add_lshl_u32 v3, v7, v13, 1
	s_waitcnt vmcnt(0)
	v_lshl_add_u32 v130, v6, 11, v3
	v_lshl_add_u32 v132, v5, 11, v3
	v_bfe_i32 v3, v234, 27, 1
	v_lshrrev_b32_e32 v3, 22, v3
	v_add_u32_e32 v3, v2, v3
	v_and_b32_e32 v3, 0xfffffc00, v3
	v_sub_u32_e32 v2, v2, v3
	v_lshrrev_b32_e32 v3, 4, v2
	v_ashrrev_i32_e32 v4, 31, v234
	v_bitop3_b32 v2, v3, v2, 32 bitop3:0x6c
	v_lshrrev_b32_e32 v4, 26, v4
	v_ashrrev_i32_e32 v3, 31, v2
	v_add_u32_e32 v4, v234, v4
	v_lshrrev_b32_e32 v3, 26, v3
	v_ashrrev_i32_e32 v15, 6, v4
	v_add_u32_e32 v3, v2, v3
	v_lshlrev_b32_e32 v4, 3, v15
	s_add_u32 s26, s0, 0x4980000
	v_ashrrev_i32_e32 v14, 6, v3
	v_and_b32_e32 v4, -16, v4
	s_addc_u32 s27, s1, 0
	v_add_u32_e32 v4, v14, v4
	v_and_b32_e32 v5, 3, v14
	s_ashr_i32 s29, s52, 31
	v_and_or_b32 v5, v4, s4, v5
	s_lshr_b32 s4, s29, 29
	s_add_i32 s4, s52, s4
	s_ashr_i32 s8, s5, 6
	s_ashr_i32 s6, s4, 3
	s_and_b32 s4, s4, -8
	s_ashr_i32 s9, s5, 8
	s_lshl_b32 s28, s8, 10
	s_sub_i32 s4, s52, s4
	s_cmp_lt_i32 s4, 0
	s_cselect_b32 s7, s49, 0x60
	s_mul_i32 s4, s4, s7
	s_add_i32 s4, s4, s6
	s_mul_hi_i32 s6, s4, 0x2aaaaaab
	s_lshr_b32 s7, s6, 31
	s_ashr_i32 s6, s6, 4
	s_add_i32 s6, s6, s7
	s_lshl_b32 s7, s6, 3
	s_mulk_i32 s6, 0x60
	s_sub_i32 s6, s4, s6
	s_bfe_i32 s4, s6, 0x80000
	s_bfe_u32 s4, s4, 0x3000c
	s_add_i32 s10, s6, s4
	s_bfe_i32 s4, s10, 0x80000
	s_and_b32 s10, s10, 0xf8
	s_sub_i32 s6, s6, s10
	s_sext_i32_i16 s4, s4
	s_sext_i32_i8 s6, s6
	v_lshrrev_b32_e32 v6, 2, v4
	v_lshlrev_b32_e32 v7, 1, v4
	v_and_b32_e32 v3, 0xc0, v3
	s_lshr_b32 s4, s4, 3
	s_add_i32 s18, s7, s6
	v_and_b32_e32 v6, 4, v6
	v_and_b32_e32 v7, 24, v7
	v_sub_u32_e32 v2, v2, v3
	s_ashr_i32 s19, s18, 31
	s_bfe_i64 s[10:11], s[4:5], 0x100000
	v_or3_b32 v5, v5, v6, v7
	v_lshlrev_b32_e32 v6, 5, v15
	v_ashrrev_i16_sdwa v2, v226, sext(v2) dst_sel:DWORD dst_unused:UNUSED_PAD src0_sel:DWORD src1_sel:BYTE_0
	s_lshl_b64 s[6:7], s[18:19], 19
	s_lshl_b64 s[10:11], s[10:11], 19
	v_and_b32_e32 v11, 15, v233
	v_and_b32_e32 v6, 32, v6
	v_bfe_i32 v16, v2, 0, 16
	s_add_u32 s20, s26, s10
	v_lshl_or_b32 v1, s9, 6, v11
	v_add_lshl_u32 v2, v6, v16, 1
	s_addc_u32 s21, s27, s11
	s_lshl_b32 s10, s18, 8
	v_lshl_add_u32 v134, v5, 11, v2
	v_lshl_add_u32 v136, v4, 11, v2
	v_add_u32_e32 v2, s10, v1
	v_or_b32_e32 v152, 16, v1
	v_or_b32_e32 v153, 32, v1
	v_or_b32_e32 v154, 48, v1
	v_add_u32_e32 v155, 0x80, v1
	v_add_u32_e32 v156, 0x90, v1
	v_add_u32_e32 v157, 0xa0, v1
	v_add_u32_e32 v158, 0xb0, v1
	v_ashrrev_i32_e32 v3, 31, v2
	v_add_u32_e32 v4, s10, v152
	v_add_u32_e32 v6, s10, v153
	v_add_u32_e32 v8, s10, v154
	v_add_u32_e32 v18, s10, v155
	v_add_u32_e32 v20, s10, v156
	v_add_u32_e32 v22, s10, v157
	v_add_u32_e32 v24, s10, v158
	s_add_i32 s30, s28, 0
	v_lshl_add_u64 v[2:3], v[2:3], 2, s[78:79]
	v_ashrrev_i32_e32 v5, 31, v4
	v_ashrrev_i32_e32 v7, 31, v6
	v_ashrrev_i32_e32 v9, 31, v8
	v_ashrrev_i32_e32 v19, 31, v18
	v_ashrrev_i32_e32 v21, 31, v20
	v_ashrrev_i32_e32 v23, 31, v22
	v_ashrrev_i32_e32 v25, 31, v24
	s_add_i32 m0, s30, 0x10000
	v_lshl_add_u64 v[4:5], v[4:5], 2, s[78:79]
	v_lshl_add_u64 v[6:7], v[6:7], 2, s[78:79]
	v_lshl_add_u64 v[8:9], v[8:9], 2, s[78:79]
	v_lshl_add_u64 v[18:19], v[18:19], 2, s[78:79]
	v_lshl_add_u64 v[20:21], v[20:21], 2, s[78:79]
	v_lshl_add_u64 v[22:23], v[22:23], 2, s[78:79]
	v_lshl_add_u64 v[24:25], v[24:25], 2, s[78:79]
	global_load_dword v149, v[2:3], off
	global_load_dword v148, v[4:5], off
	global_load_dword v147, v[6:7], off
	global_load_dword v146, v[8:9], off
	global_load_dword v145, v[18:19], off
	global_load_dword v143, v[20:21], off
	global_load_dword v142, v[22:23], off
	global_load_dword v144, v[24:25], off
	v_mov_b32_e32 v135, v0
	global_load_lds_dwordx4 v134, s[20:21]
	s_add_i32 m0, s30, 0x12000
	s_add_u32 s10, s20, 0x40000
	global_load_lds_dwordx4 v130, s[20:21]
	s_addc_u32 s11, s21, 0
	s_add_i32 m0, s30, 0x14000
	v_mov_b32_e32 v131, v0
	global_load_lds_dwordx4 v134, s[10:11]
	s_add_i32 m0, s30, 0x16000
	s_add_u32 s22, s80, s6
	s_addc_u32 s23, s81, s7
	s_add_i32 s31, s30, 0x2000
	global_load_lds_dwordx4 v130, s[10:11]
	s_mov_b32 m0, s30
	s_add_u32 s6, s22, 0x40000
	global_load_lds_dwordx4 v136, s[22:23]
	s_mov_b32 m0, s31
	s_addc_u32 s7, s23, 0
	s_add_i32 s34, s30, 0x4000
	global_load_lds_dwordx4 v132, s[22:23]
	s_mov_b32 m0, s34
	s_add_i32 s35, s30, 0x6000
	global_load_lds_dwordx4 v136, s[6:7]
	s_mov_b32 m0, s35
	v_mov_b32_e32 v137, v0
	global_load_lds_dwordx4 v132, s[6:7]
	v_mov_b32_e32 v133, v0
	s_cmp_eq_u32 s9, 1
	v_lshl_add_u64 v[8:9], s[20:21], 0, v[134:135]
	v_lshl_add_u64 v[6:7], s[20:21], 0, v[130:131]
	v_lshl_add_u64 v[2:3], s[22:23], 0, v[136:137]
	s_cselect_b64 s[6:7], -1, 0
	s_cmp_lg_u32 s9, 1
	v_lshl_add_u64 v[4:5], s[22:23], 0, v[132:133]
	s_cbranch_scc1 .LBB0_634
	s_setprio 1
	s_barrier

.LBB0_640:
	s_add_u32 s22, s20, 0xfffc0080
	s_addc_u32 s23, s21, -1
	s_add_i32 s46, 0, 0x10000
	s_cmp_eq_u32 s45, 12
	s_cselect_b32 s25, s13, s23
	s_cselect_b32 s24, s19, s22
	v_add_u32_e32 v150, s46, v159
	s_cselect_b32 s23, s11, s44
	s_cselect_b32 s22, s41, s43
	s_add_i32 s48, 0, 0x14000
	ds_read_b128 v[164:167], v150
	ds_read_b128 v[168:171], v150 offset:1024
	ds_read_b128 v[172:175], v150 offset:2048
	ds_read_b128 v[176:179], v150 offset:3072
	v_add_u32_e32 v150, s48, v159
	ds_read_b128 v[180:183], v150
	ds_read_b128 v[184:187], v150 offset:1024
	ds_read_b128 v[188:191], v150 offset:2048
	ds_read_b128 v[192:195], v150 offset:3072
	v_lshl_add_u64 v[150:151], s[20:21], 0, v[140:141]
	s_add_i32 m0, s30, 0xc000
	ds_read_b128 v[196:199], v162
	ds_read_b128 v[200:203], v162 offset:1024
	ds_read_b128 v[204:207], v162 offset:2048
	ds_read_b128 v[220:223], v162 offset:3072
	ds_read_b128 v[236:239], v162 offset:4096
	ds_read_b128 v[240:243], v162 offset:5120
	ds_read_b128 v[244:247], v162 offset:6144
	ds_read_b128 v[248:251], v162 offset:7168
	global_load_lds_dwordx4 v[150:151], off
	v_lshl_add_u64 v[150:151], s[20:21], 0, v[138:139]
	s_add_i32 m0, s30, 0xe000
	s_nop 0
	global_load_lds_dwordx4 v[150:151], off
	s_waitcnt vmcnt(8)
	s_waitcnt lgkmcnt(0)
	s_barrier
	s_waitcnt lgkmcnt(0)
	v_mfma_f32_16x16x32_bf16 v[126:129], v[164:167], v[196:199], v[126:129]
	v_mfma_f32_16x16x32_bf16 v[122:125], v[172:175], v[196:199], v[122:125]
	v_mfma_f32_16x16x32_bf16 v[118:121], v[164:167], v[204:207], v[118:121]
	v_mfma_f32_16x16x32_bf16 v[114:117], v[172:175], v[204:207], v[114:117]
	v_mfma_f32_16x16x32_bf16 v[110:113], v[164:167], v[236:239], v[110:113]
	v_mfma_f32_16x16x32_bf16 v[106:109], v[172:175], v[236:239], v[106:109]
	v_mfma_f32_16x16x32_bf16 v[102:105], v[164:167], v[244:247], v[102:105]
	v_mfma_f32_16x16x32_bf16 v[98:101], v[172:175], v[244:247], v[98:101]
	v_mfma_f32_16x16x32_bf16 v[126:129], v[168:171], v[200:203], v[126:129]
	v_mfma_f32_16x16x32_bf16 v[122:125], v[176:179], v[200:203], v[122:125]
	v_mfma_f32_16x16x32_bf16 v[118:121], v[168:171], v[220:223], v[118:121]
	v_mfma_f32_16x16x32_bf16 v[114:117], v[176:179], v[220:223], v[114:117]
	v_mfma_f32_16x16x32_bf16 v[110:113], v[168:171], v[240:243], v[110:113]
	v_mfma_f32_16x16x32_bf16 v[106:109], v[176:179], v[240:243], v[106:109]
	v_mfma_f32_16x16x32_bf16 v[102:105], v[168:171], v[248:251], v[102:105]
	v_mfma_f32_16x16x32_bf16 v[98:101], v[176:179], v[248:251], v[98:101]
	v_mfma_f32_16x16x32_bf16 v[94:97], v[180:183], v[196:199], v[94:97]
	v_mfma_f32_16x16x32_bf16 v[90:93], v[188:191], v[196:199], v[90:93]
	v_mfma_f32_16x16x32_bf16 v[86:89], v[180:183], v[204:207], v[86:89]
	v_mfma_f32_16x16x32_bf16 v[82:85], v[188:191], v[204:207], v[82:85]
	v_mfma_f32_16x16x32_bf16 v[78:81], v[180:183], v[236:239], v[78:81]
	v_mfma_f32_16x16x32_bf16 v[74:77], v[188:191], v[236:239], v[74:77]
	v_mfma_f32_16x16x32_bf16 v[70:73], v[180:183], v[244:247], v[70:73]
	v_mfma_f32_16x16x32_bf16 v[66:69], v[188:191], v[244:247], v[66:69]
	v_mfma_f32_16x16x32_bf16 v[94:97], v[184:187], v[200:203], v[94:97]
	v_mfma_f32_16x16x32_bf16 v[90:93], v[192:195], v[200:203], v[90:93]
	v_mfma_f32_16x16x32_bf16 v[86:89], v[184:187], v[220:223], v[86:89]
	v_mfma_f32_16x16x32_bf16 v[82:85], v[192:195], v[220:223], v[82:85]
	v_mfma_f32_16x16x32_bf16 v[78:81], v[184:187], v[240:243], v[78:81]
	v_mfma_f32_16x16x32_bf16 v[74:77], v[192:195], v[240:243], v[74:77]
	v_mfma_f32_16x16x32_bf16 v[70:73], v[184:187], v[248:251], v[70:73]
	v_mfma_f32_16x16x32_bf16 v[66:69], v[192:195], v[248:251], v[66:69]
	s_barrier
	s_add_i32 s46, s46, s28
	v_lshl_add_u64 v[150:151], s[22:23], 0, v[134:135]
	s_mov_b32 m0, s46
	ds_read_b128 v[196:199], v162 offset:16384
	ds_read_b128 v[200:203], v162 offset:17408
	ds_read_b128 v[204:207], v162 offset:18432
	ds_read_b128 v[220:223], v162 offset:19456
	ds_read_b128 v[236:239], v162 offset:20480
	ds_read_b128 v[240:243], v162 offset:21504
	ds_read_b128 v[244:247], v162 offset:22528
	ds_read_b128 v[248:251], v162 offset:23552
	global_load_lds_dwordx4 v[150:151], off
	s_add_i32 m0, s46, 0x2000
	s_add_u32 s46, s22, 0x40000
	v_lshl_add_u64 v[208:209], s[22:23], 0, v[130:131]
	s_addc_u32 s47, s23, 0
	s_add_i32 s48, s48, s28
	global_load_lds_dwordx4 v[208:209], off
	v_lshl_add_u64 v[224:225], s[46:47], 0, v[134:135]
	s_mov_b32 m0, s48
	v_lshl_add_u64 v[252:253], s[24:25], 0, v[132:133]
	global_load_lds_dwordx4 v[224:225], off
	v_lshl_add_u64 v[224:225], s[46:47], 0, v[130:131]
	s_add_i32 m0, s48, 0x2000
	s_nop 0
	global_load_lds_dwordx4 v[224:225], off
	v_lshl_add_u64 v[224:225], s[24:25], 0, v[136:137]
	s_mov_b32 m0, s30
	s_nop 0
	global_load_lds_dwordx4 v[224:225], off
	s_mov_b32 m0, s31
	s_nop 0
	global_load_lds_dwordx4 v[252:253], off
	s_waitcnt vmcnt(8)
	s_waitcnt lgkmcnt(0)
	s_barrier
	s_waitcnt lgkmcnt(0)
	v_mfma_f32_16x16x32_bf16 v[62:65], v[164:167], v[196:199], v[62:65]
	v_mfma_f32_16x16x32_bf16 v[58:61], v[172:175], v[196:199], v[58:61]
	v_mfma_f32_16x16x32_bf16 v[54:57], v[164:167], v[204:207], v[54:57]
	v_mfma_f32_16x16x32_bf16 v[50:53], v[172:175], v[204:207], v[50:53]
	v_mfma_f32_16x16x32_bf16 v[46:49], v[164:167], v[236:239], v[46:49]
	v_mfma_f32_16x16x32_bf16 v[42:45], v[172:175], v[236:239], v[42:45]
	v_mfma_f32_16x16x32_bf16 v[38:41], v[164:167], v[244:247], v[38:41]
	v_mfma_f32_16x16x32_bf16 v[34:37], v[172:175], v[244:247], v[34:37]
	v_mfma_f32_16x16x32_bf16 v[62:65], v[168:171], v[200:203], v[62:65]
	v_mfma_f32_16x16x32_bf16 v[58:61], v[176:179], v[200:203], v[58:61]
	v_mfma_f32_16x16x32_bf16 v[54:57], v[168:171], v[220:223], v[54:57]
	v_mfma_f32_16x16x32_bf16 v[50:53], v[176:179], v[220:223], v[50:53]
	v_mfma_f32_16x16x32_bf16 v[46:49], v[168:171], v[240:243], v[46:49]
	v_mfma_f32_16x16x32_bf16 v[42:45], v[176:179], v[240:243], v[42:45]
	v_mfma_f32_16x16x32_bf16 v[38:41], v[168:171], v[248:251], v[38:41]
	v_mfma_f32_16x16x32_bf16 v[34:37], v[176:179], v[248:251], v[34:37]
	v_mfma_f32_16x16x32_bf16 v[30:33], v[180:183], v[196:199], v[30:33]
	v_mfma_f32_16x16x32_bf16 v[26:29], v[188:191], v[196:199], v[26:29]
	v_mfma_f32_16x16x32_bf16 v[22:25], v[180:183], v[204:207], v[22:25]
	v_mfma_f32_16x16x32_bf16 v[18:21], v[188:191], v[204:207], v[18:21]
	v_mfma_f32_16x16x32_bf16 v[14:17], v[180:183], v[236:239], v[14:17]
	v_mfma_f32_16x16x32_bf16 v[10:13], v[188:191], v[236:239], v[10:13]
	v_mfma_f32_16x16x32_bf16 v[6:9], v[180:183], v[244:247], v[6:9]
	v_mfma_f32_16x16x32_bf16 v[2:5], v[188:191], v[244:247], v[2:5]
	v_mfma_f32_16x16x32_bf16 v[30:33], v[184:187], v[200:203], v[30:33]
	v_mfma_f32_16x16x32_bf16 v[26:29], v[192:195], v[200:203], v[26:29]
	v_mfma_f32_16x16x32_bf16 v[22:25], v[184:187], v[220:223], v[22:25]
	v_mfma_f32_16x16x32_bf16 v[18:21], v[192:195], v[220:223], v[18:21]
	v_mfma_f32_16x16x32_bf16 v[14:17], v[184:187], v[240:243], v[14:17]
	v_mfma_f32_16x16x32_bf16 v[10:13], v[192:195], v[240:243], v[10:13]
	v_mfma_f32_16x16x32_bf16 v[6:9], v[184:187], v[248:251], v[6:9]
	v_mfma_f32_16x16x32_bf16 v[2:5], v[192:195], v[248:251], v[2:5]
	s_barrier
	s_add_i32 s46, 0, 0x18000
	v_add_u32_e32 v163, s46, v159
	s_add_i32 s47, 0, 0x1c000
	ds_read_b128 v[164:167], v163
	ds_read_b128 v[168:171], v163 offset:1024
	ds_read_b128 v[172:175], v163 offset:2048
	ds_read_b128 v[176:179], v163 offset:3072
	v_add_u32_e32 v163, s47, v159
	ds_read_b128 v[180:183], v163
	ds_read_b128 v[184:187], v163 offset:1024
	ds_read_b128 v[188:191], v163 offset:2048
	ds_read_b128 v[192:195], v163 offset:3072
	s_add_u32 s24, s24, 0x40000
	s_addc_u32 s25, s25, 0
	s_mov_b32 m0, s34
	v_lshl_add_u64 v[230:231], s[24:25], 0, v[136:137]
	ds_read_b128 v[196:199], v162 offset:32768
	ds_read_b128 v[200:203], v162 offset:33792
	ds_read_b128 v[204:207], v162 offset:34816
	ds_read_b128 v[220:223], v162 offset:35840
	ds_read_b128 v[236:239], v162 offset:36864
	ds_read_b128 v[240:243], v162 offset:37888
	ds_read_b128 v[244:247], v162 offset:38912
	ds_read_b128 v[248:251], v162 offset:39936
	global_load_lds_dwordx4 v[230:231], off
	v_lshl_add_u64 v[230:231], s[24:25], 0, v[132:133]
	s_mov_b32 m0, s35
	s_nop 0
	global_load_lds_dwordx4 v[230:231], off
	s_waitcnt vmcnt(8)
	s_waitcnt lgkmcnt(0)
	s_barrier
	s_waitcnt lgkmcnt(0)
	v_mfma_f32_16x16x32_bf16 v[126:129], v[164:167], v[196:199], v[126:129]
	v_mfma_f32_16x16x32_bf16 v[122:125], v[172:175], v[196:199], v[122:125]
	v_mfma_f32_16x16x32_bf16 v[118:121], v[164:167], v[204:207], v[118:121]
	v_mfma_f32_16x16x32_bf16 v[114:117], v[172:175], v[204:207], v[114:117]
	v_mfma_f32_16x16x32_bf16 v[110:113], v[164:167], v[236:239], v[110:113]
	v_mfma_f32_16x16x32_bf16 v[106:109], v[172:175], v[236:239], v[106:109]
	v_mfma_f32_16x16x32_bf16 v[102:105], v[164:167], v[244:247], v[102:105]
	v_mfma_f32_16x16x32_bf16 v[98:101], v[172:175], v[244:247], v[98:101]
	v_mfma_f32_16x16x32_bf16 v[126:129], v[168:171], v[200:203], v[126:129]
	v_mfma_f32_16x16x32_bf16 v[122:125], v[176:179], v[200:203], v[122:125]
	v_mfma_f32_16x16x32_bf16 v[118:121], v[168:171], v[220:223], v[118:121]
	v_mfma_f32_16x16x32_bf16 v[114:117], v[176:179], v[220:223], v[114:117]
	v_mfma_f32_16x16x32_bf16 v[110:113], v[168:171], v[240:243], v[110:113]
	v_mfma_f32_16x16x32_bf16 v[106:109], v[176:179], v[240:243], v[106:109]
	v_mfma_f32_16x16x32_bf16 v[102:105], v[168:171], v[248:251], v[102:105]
	v_mfma_f32_16x16x32_bf16 v[98:101], v[176:179], v[248:251], v[98:101]
	v_mfma_f32_16x16x32_bf16 v[94:97], v[180:183], v[196:199], v[94:97]
	v_mfma_f32_16x16x32_bf16 v[90:93], v[188:191], v[196:199], v[90:93]
	v_mfma_f32_16x16x32_bf16 v[86:89], v[180:183], v[204:207], v[86:89]
	v_mfma_f32_16x16x32_bf16 v[82:85], v[188:191], v[204:207], v[82:85]
	v_mfma_f32_16x16x32_bf16 v[78:81], v[180:183], v[236:239], v[78:81]
	v_mfma_f32_16x16x32_bf16 v[74:77], v[188:191], v[236:239], v[74:77]
	v_mfma_f32_16x16x32_bf16 v[70:73], v[180:183], v[244:247], v[70:73]
	v_mfma_f32_16x16x32_bf16 v[66:69], v[188:191], v[244:247], v[66:69]
	v_mfma_f32_16x16x32_bf16 v[94:97], v[184:187], v[200:203], v[94:97]
	v_mfma_f32_16x16x32_bf16 v[90:93], v[192:195], v[200:203], v[90:93]
	v_mfma_f32_16x16x32_bf16 v[86:89], v[184:187], v[220:223], v[86:89]
	v_mfma_f32_16x16x32_bf16 v[82:85], v[192:195], v[220:223], v[82:85]
	v_mfma_f32_16x16x32_bf16 v[78:81], v[184:187], v[240:243], v[78:81]
	v_mfma_f32_16x16x32_bf16 v[74:77], v[192:195], v[240:243], v[74:77]
	v_mfma_f32_16x16x32_bf16 v[70:73], v[184:187], v[248:251], v[70:73]
	v_mfma_f32_16x16x32_bf16 v[66:69], v[192:195], v[248:251], v[66:69]
	s_barrier
	s_add_i32 s24, s46, s28
	v_lshl_add_u64 v[150:151], v[150:151], 0, s[96:97]
	s_mov_b32 m0, s24
	ds_read_b128 v[196:199], v162 offset:49152
	ds_read_b128 v[200:203], v162 offset:50176
	ds_read_b128 v[204:207], v162 offset:51200
	ds_read_b128 v[220:223], v162 offset:52224
	ds_read_b128 v[236:239], v162 offset:53248
	ds_read_b128 v[240:243], v162 offset:54272
	ds_read_b128 v[244:247], v162 offset:55296
	ds_read_b128 v[248:251], v162 offset:56320
	global_load_lds_dwordx4 v[150:151], off
	s_add_i32 m0, s24, 0x2000
	s_add_u32 s22, s22, 0x40080
	v_lshl_add_u64 v[150:151], v[208:209], 0, s[96:97]
	s_addc_u32 s23, s23, 0
	s_add_i32 s24, s47, s28
	global_load_lds_dwordx4 v[150:151], off
	v_lshl_add_u64 v[150:151], s[22:23], 0, v[134:135]
	s_mov_b32 m0, s24
	s_nop 0
	global_load_lds_dwordx4 v[150:151], off
	v_lshl_add_u64 v[150:151], s[22:23], 0, v[130:131]
	s_add_i32 m0, s24, 0x2000
	s_nop 0
	global_load_lds_dwordx4 v[150:151], off
	v_lshl_add_u64 v[150:151], v[224:225], 0, s[96:97]
	s_mov_b32 m0, s36
	s_nop 0
	global_load_lds_dwordx4 v[150:151], off
	v_lshl_add_u64 v[150:151], v[252:253], 0, s[96:97]
	s_mov_b32 m0, s37
	s_nop 0
	global_load_lds_dwordx4 v[150:151], off
	s_waitcnt vmcnt(8)
	s_waitcnt lgkmcnt(0)
	s_barrier
	s_waitcnt lgkmcnt(0)
	v_mfma_f32_16x16x32_bf16 v[62:65], v[164:167], v[196:199], v[62:65]
	v_mfma_f32_16x16x32_bf16 v[58:61], v[172:175], v[196:199], v[58:61]
	v_mfma_f32_16x16x32_bf16 v[54:57], v[164:167], v[204:207], v[54:57]
	v_mfma_f32_16x16x32_bf16 v[50:53], v[172:175], v[204:207], v[50:53]
	v_mfma_f32_16x16x32_bf16 v[46:49], v[164:167], v[236:239], v[46:49]
	v_mfma_f32_16x16x32_bf16 v[42:45], v[172:175], v[236:239], v[42:45]
	v_mfma_f32_16x16x32_bf16 v[38:41], v[164:167], v[244:247], v[38:41]
	v_mfma_f32_16x16x32_bf16 v[34:37], v[172:175], v[244:247], v[34:37]
	v_mfma_f32_16x16x32_bf16 v[62:65], v[168:171], v[200:203], v[62:65]
	v_mfma_f32_16x16x32_bf16 v[58:61], v[176:179], v[200:203], v[58:61]
	v_mfma_f32_16x16x32_bf16 v[54:57], v[168:171], v[220:223], v[54:57]
	v_mfma_f32_16x16x32_bf16 v[50:53], v[176:179], v[220:223], v[50:53]
	v_mfma_f32_16x16x32_bf16 v[46:49], v[168:171], v[240:243], v[46:49]
	v_mfma_f32_16x16x32_bf16 v[42:45], v[176:179], v[240:243], v[42:45]
	v_mfma_f32_16x16x32_bf16 v[38:41], v[168:171], v[248:251], v[38:41]
	v_mfma_f32_16x16x32_bf16 v[34:37], v[176:179], v[248:251], v[34:37]
	v_mfma_f32_16x16x32_bf16 v[30:33], v[180:183], v[196:199], v[30:33]
	v_mfma_f32_16x16x32_bf16 v[26:29], v[188:191], v[196:199], v[26:29]
	v_mfma_f32_16x16x32_bf16 v[22:25], v[180:183], v[204:207], v[22:25]
	v_mfma_f32_16x16x32_bf16 v[18:21], v[188:191], v[204:207], v[18:21]
	v_mfma_f32_16x16x32_bf16 v[14:17], v[180:183], v[236:239], v[14:17]
	v_mfma_f32_16x16x32_bf16 v[10:13], v[188:191], v[236:239], v[10:13]
	v_mfma_f32_16x16x32_bf16 v[6:9], v[180:183], v[244:247], v[6:9]
	v_mfma_f32_16x16x32_bf16 v[2:5], v[188:191], v[244:247], v[2:5]
	v_mfma_f32_16x16x32_bf16 v[30:33], v[184:187], v[200:203], v[30:33]
	v_mfma_f32_16x16x32_bf16 v[26:29], v[192:195], v[200:203], v[26:29]
	v_mfma_f32_16x16x32_bf16 v[22:25], v[184:187], v[220:223], v[22:25]
	v_mfma_f32_16x16x32_bf16 v[18:21], v[192:195], v[220:223], v[18:21]
	v_mfma_f32_16x16x32_bf16 v[14:17], v[184:187], v[240:243], v[14:17]
	v_mfma_f32_16x16x32_bf16 v[10:13], v[192:195], v[240:243], v[10:13]
	v_mfma_f32_16x16x32_bf16 v[6:9], v[184:187], v[248:251], v[6:9]
	v_mfma_f32_16x16x32_bf16 v[2:5], v[192:195], v[248:251], v[2:5]
	s_barrier
	s_add_i32 s45, s45, 2
	s_add_u32 s43, s43, 0x100
	s_addc_u32 s44, s44, 0
	s_add_u32 s20, s20, 0x100
	s_addc_u32 s21, s21, 0
	s_cmp_gt_u32 s45, 13
	s_cbranch_scc0 .LBB0_640
	s_and_b64 vcc, exec, s[8:9]
	s_cbranch_vccz .LBB0_643
	s_barrier
